# GEMM K-loops: only the ds_read bursts of each load segment run at raised priority (no other priority flips), on top of v46
# speedup vs baseline: 1.0035x; 1.0017x over previous
.LBB0_577:
	s_setprio 2
	ds_read_b128 v[128:131], v193
	ds_read_b128 v[132:135], v193 offset:1024
	ds_read_b128 v[136:139], v193 offset:2048
	ds_read_b128 v[140:143], v193 offset:3072
	ds_read_b128 v[144:147], v194
	ds_read_b128 v[148:151], v194 offset:1024
	ds_read_b128 v[152:155], v194 offset:2048
	ds_read_b128 v[156:159], v194 offset:3072
	s_add_u32 s35, s42, 0xfff80080
	s_addc_u32 s39, s43, -1
	s_cmp_eq_u32 s31, 4
	s_cselect_b32 s47, s1, s39
	s_cselect_b32 s46, s0, s35
	s_cselect_b32 s45, s37, s23
	s_cselect_b32 s44, s36, s11
	v_lshl_add_u64 v[218:219], s[42:43], 0, v[168:169]
	s_add_i32 m0, s7, 0xc000
	ds_read_b128 v[176:179], v195
	ds_read_b128 v[180:183], v195 offset:1024
	ds_read_b128 v[184:187], v195 offset:2048
	ds_read_b128 v[198:201], v195 offset:3072
	ds_read_b128 v[202:205], v195 offset:4096
	ds_read_b128 v[206:209], v195 offset:5120
	ds_read_b128 v[210:213], v195 offset:6144
	ds_read_b128 v[214:217], v195 offset:7168
	s_setprio 0
	global_load_lds_dwordx4 v[218:219], off
	v_lshl_add_u64 v[218:219], s[42:43], 0, v[170:171]
	s_add_i32 m0, s7, 0xe000
	s_nop 0
	global_load_lds_dwordx4 v[218:219], off
	s_waitcnt vmcnt(8)
	s_waitcnt lgkmcnt(0)
	s_barrier
	s_waitcnt lgkmcnt(0)
	v_mfma_f32_16x16x32_bf16 v[124:127], v[128:131], v[176:179], v[124:127]
	v_mfma_f32_16x16x32_bf16 v[120:123], v[136:139], v[176:179], v[120:123]
	v_mfma_f32_16x16x32_bf16 v[108:111], v[128:131], v[184:187], v[108:111]
	v_mfma_f32_16x16x32_bf16 v[104:107], v[136:139], v[184:187], v[104:107]
	v_mfma_f32_16x16x32_bf16 v[92:95], v[128:131], v[202:205], v[92:95]
	v_mfma_f32_16x16x32_bf16 v[88:91], v[136:139], v[202:205], v[88:91]
	v_mfma_f32_16x16x32_bf16 v[76:79], v[128:131], v[210:213], v[76:79]
	v_mfma_f32_16x16x32_bf16 v[72:75], v[136:139], v[210:213], v[72:75]
	v_mfma_f32_16x16x32_bf16 v[124:127], v[132:135], v[180:183], v[124:127]
	v_mfma_f32_16x16x32_bf16 v[120:123], v[140:143], v[180:183], v[120:123]
	v_mfma_f32_16x16x32_bf16 v[108:111], v[132:135], v[198:201], v[108:111]
	v_mfma_f32_16x16x32_bf16 v[104:107], v[140:143], v[198:201], v[104:107]
	v_mfma_f32_16x16x32_bf16 v[92:95], v[132:135], v[206:209], v[92:95]
	v_mfma_f32_16x16x32_bf16 v[88:91], v[140:143], v[206:209], v[88:91]
	v_mfma_f32_16x16x32_bf16 v[76:79], v[132:135], v[214:217], v[76:79]
	v_mfma_f32_16x16x32_bf16 v[72:75], v[140:143], v[214:217], v[72:75]
	v_mfma_f32_16x16x32_bf16 v[116:119], v[144:147], v[176:179], v[116:119]
	v_mfma_f32_16x16x32_bf16 v[112:115], v[152:155], v[176:179], v[112:115]
	v_mfma_f32_16x16x32_bf16 v[100:103], v[144:147], v[184:187], v[100:103]
	v_mfma_f32_16x16x32_bf16 v[96:99], v[152:155], v[184:187], v[96:99]
	v_mfma_f32_16x16x32_bf16 v[84:87], v[144:147], v[202:205], v[84:87]
	v_mfma_f32_16x16x32_bf16 v[80:83], v[152:155], v[202:205], v[80:83]
	v_mfma_f32_16x16x32_bf16 v[68:71], v[144:147], v[210:213], v[68:71]
	v_mfma_f32_16x16x32_bf16 v[64:67], v[152:155], v[210:213], v[64:67]
	v_mfma_f32_16x16x32_bf16 v[116:119], v[148:151], v[180:183], v[116:119]
	v_mfma_f32_16x16x32_bf16 v[112:115], v[156:159], v[180:183], v[112:115]
	v_mfma_f32_16x16x32_bf16 v[100:103], v[148:151], v[198:201], v[100:103]
	v_mfma_f32_16x16x32_bf16 v[96:99], v[156:159], v[198:201], v[96:99]
	v_mfma_f32_16x16x32_bf16 v[84:87], v[148:151], v[206:209], v[84:87]
	v_mfma_f32_16x16x32_bf16 v[80:83], v[156:159], v[206:209], v[80:83]
	v_mfma_f32_16x16x32_bf16 v[68:71], v[148:151], v[214:217], v[68:71]
	v_mfma_f32_16x16x32_bf16 v[64:67], v[156:159], v[214:217], v[64:67]
	s_barrier
	s_add_i32 s35, s48, s6
	v_lshl_add_u64 v[218:219], s[44:45], 0, v[162:163]
	s_mov_b32 m0, s35
	s_setprio 2
	ds_read_b128 v[176:179], v195 offset:16384
	ds_read_b128 v[180:183], v195 offset:17408
	ds_read_b128 v[184:187], v195 offset:18432
	ds_read_b128 v[198:201], v195 offset:19456
	ds_read_b128 v[202:205], v195 offset:20480
	ds_read_b128 v[206:209], v195 offset:21504
	ds_read_b128 v[210:213], v195 offset:22528
	ds_read_b128 v[214:217], v195 offset:23552
	s_setprio 0
	global_load_lds_dwordx4 v[218:219], off
	s_add_i32 m0, s35, 0x2000
	s_add_u32 s50, s44, 0x20000
	v_lshl_add_u64 v[220:221], s[44:45], 0, v[166:167]
	s_addc_u32 s51, s45, 0
	s_add_i32 s35, s49, s6
	global_load_lds_dwordx4 v[220:221], off
	v_lshl_add_u64 v[222:223], s[50:51], 0, v[162:163]
	s_mov_b32 m0, s35
	v_lshl_add_u64 v[224:225], s[46:47], 0, v[164:165]
	global_load_lds_dwordx4 v[222:223], off
	v_lshl_add_u64 v[222:223], s[50:51], 0, v[166:167]
	s_add_i32 m0, s35, 0x2000
	s_nop 0
	global_load_lds_dwordx4 v[222:223], off
	v_lshl_add_u64 v[222:223], s[46:47], 0, v[160:161]
	s_mov_b32 m0, s7
	s_nop 0
	global_load_lds_dwordx4 v[222:223], off
	s_mov_b32 m0, s8
	s_nop 0
	global_load_lds_dwordx4 v[224:225], off
	s_waitcnt vmcnt(8)
	s_waitcnt lgkmcnt(0)
	s_barrier
	s_waitcnt lgkmcnt(0)
	v_mfma_f32_16x16x32_bf16 v[60:63], v[128:131], v[176:179], v[60:63]
	v_mfma_f32_16x16x32_bf16 v[56:59], v[136:139], v[176:179], v[56:59]
	v_mfma_f32_16x16x32_bf16 v[44:47], v[128:131], v[184:187], v[44:47]
	v_mfma_f32_16x16x32_bf16 v[40:43], v[136:139], v[184:187], v[40:43]
	v_mfma_f32_16x16x32_bf16 v[28:31], v[128:131], v[202:205], v[28:31]
	v_mfma_f32_16x16x32_bf16 v[24:27], v[136:139], v[202:205], v[24:27]
	v_mfma_f32_16x16x32_bf16 v[12:15], v[128:131], v[210:213], v[12:15]
	v_mfma_f32_16x16x32_bf16 v[8:11], v[136:139], v[210:213], v[8:11]
	v_mfma_f32_16x16x32_bf16 v[60:63], v[132:135], v[180:183], v[60:63]
	v_mfma_f32_16x16x32_bf16 v[56:59], v[140:143], v[180:183], v[56:59]
	v_mfma_f32_16x16x32_bf16 v[44:47], v[132:135], v[198:201], v[44:47]
	v_mfma_f32_16x16x32_bf16 v[40:43], v[140:143], v[198:201], v[40:43]
	v_mfma_f32_16x16x32_bf16 v[28:31], v[132:135], v[206:209], v[28:31]
	v_mfma_f32_16x16x32_bf16 v[24:27], v[140:143], v[206:209], v[24:27]
	v_mfma_f32_16x16x32_bf16 v[12:15], v[132:135], v[214:217], v[12:15]
	v_mfma_f32_16x16x32_bf16 v[8:11], v[140:143], v[214:217], v[8:11]
	v_mfma_f32_16x16x32_bf16 v[52:55], v[144:147], v[176:179], v[52:55]
	v_mfma_f32_16x16x32_bf16 v[48:51], v[152:155], v[176:179], v[48:51]
	v_mfma_f32_16x16x32_bf16 v[36:39], v[144:147], v[184:187], v[36:39]
	v_mfma_f32_16x16x32_bf16 v[32:35], v[152:155], v[184:187], v[32:35]
	v_mfma_f32_16x16x32_bf16 v[20:23], v[144:147], v[202:205], v[20:23]
	v_mfma_f32_16x16x32_bf16 v[16:19], v[152:155], v[202:205], v[16:19]
	v_mfma_f32_16x16x32_bf16 v[4:7], v[144:147], v[210:213], v[4:7]
	v_mfma_f32_16x16x32_bf16 v[0:3], v[152:155], v[210:213], v[0:3]
	v_mfma_f32_16x16x32_bf16 v[52:55], v[148:151], v[180:183], v[52:55]
	v_mfma_f32_16x16x32_bf16 v[48:51], v[156:159], v[180:183], v[48:51]
	v_mfma_f32_16x16x32_bf16 v[36:39], v[148:151], v[198:201], v[36:39]
	v_mfma_f32_16x16x32_bf16 v[32:35], v[156:159], v[198:201], v[32:35]
	v_mfma_f32_16x16x32_bf16 v[20:23], v[148:151], v[206:209], v[20:23]
	v_mfma_f32_16x16x32_bf16 v[16:19], v[156:159], v[206:209], v[16:19]
	v_mfma_f32_16x16x32_bf16 v[4:7], v[148:151], v[214:217], v[4:7]
	v_mfma_f32_16x16x32_bf16 v[0:3], v[156:159], v[214:217], v[0:3]
	s_barrier
	s_add_i32 s35, 0, 0x18000
	s_add_i32 s39, 0, 0x1c000
	v_add_u32_e32 v140, s35, v191
	v_add_u32_e32 v156, s39, v191
	s_setprio 2
	ds_read_b128 v[128:131], v140
	ds_read_b128 v[132:135], v140 offset:1024
	ds_read_b128 v[136:139], v140 offset:2048
	ds_read_b128 v[140:143], v140 offset:3072
	ds_read_b128 v[144:147], v156
	ds_read_b128 v[148:151], v156 offset:1024
	ds_read_b128 v[152:155], v156 offset:2048
	ds_read_b128 v[156:159], v156 offset:3072
	s_add_u32 s46, s46, 0x80000
	s_addc_u32 s47, s47, 0
	s_mov_b32 m0, s9
	v_lshl_add_u64 v[226:227], s[46:47], 0, v[160:161]
	ds_read_b128 v[176:179], v195 offset:32768
	ds_read_b128 v[180:183], v195 offset:33792
	ds_read_b128 v[184:187], v195 offset:34816
	ds_read_b128 v[198:201], v195 offset:35840
	ds_read_b128 v[202:205], v195 offset:36864
	ds_read_b128 v[206:209], v195 offset:37888
	ds_read_b128 v[210:213], v195 offset:38912
	ds_read_b128 v[214:217], v195 offset:39936
	s_setprio 0
	global_load_lds_dwordx4 v[226:227], off
	v_lshl_add_u64 v[226:227], s[46:47], 0, v[164:165]
	s_mov_b32 m0, s24
	s_nop 0
	global_load_lds_dwordx4 v[226:227], off
	s_waitcnt vmcnt(8)
	s_waitcnt lgkmcnt(0)
	s_barrier
	s_waitcnt lgkmcnt(0)
	v_mfma_f32_16x16x32_bf16 v[124:127], v[128:131], v[176:179], v[124:127]
	v_mfma_f32_16x16x32_bf16 v[120:123], v[136:139], v[176:179], v[120:123]
	v_mfma_f32_16x16x32_bf16 v[108:111], v[128:131], v[184:187], v[108:111]
	v_mfma_f32_16x16x32_bf16 v[104:107], v[136:139], v[184:187], v[104:107]
	v_mfma_f32_16x16x32_bf16 v[92:95], v[128:131], v[202:205], v[92:95]
	v_mfma_f32_16x16x32_bf16 v[88:91], v[136:139], v[202:205], v[88:91]
	v_mfma_f32_16x16x32_bf16 v[76:79], v[128:131], v[210:213], v[76:79]
	v_mfma_f32_16x16x32_bf16 v[72:75], v[136:139], v[210:213], v[72:75]
	v_mfma_f32_16x16x32_bf16 v[124:127], v[132:135], v[180:183], v[124:127]
	v_mfma_f32_16x16x32_bf16 v[120:123], v[140:143], v[180:183], v[120:123]
	v_mfma_f32_16x16x32_bf16 v[108:111], v[132:135], v[198:201], v[108:111]
	v_mfma_f32_16x16x32_bf16 v[104:107], v[140:143], v[198:201], v[104:107]
	v_mfma_f32_16x16x32_bf16 v[92:95], v[132:135], v[206:209], v[92:95]
	v_mfma_f32_16x16x32_bf16 v[88:91], v[140:143], v[206:209], v[88:91]
	v_mfma_f32_16x16x32_bf16 v[76:79], v[132:135], v[214:217], v[76:79]
	v_mfma_f32_16x16x32_bf16 v[72:75], v[140:143], v[214:217], v[72:75]
	v_mfma_f32_16x16x32_bf16 v[116:119], v[144:147], v[176:179], v[116:119]
	v_mfma_f32_16x16x32_bf16 v[112:115], v[152:155], v[176:179], v[112:115]
	v_mfma_f32_16x16x32_bf16 v[100:103], v[144:147], v[184:187], v[100:103]
	v_mfma_f32_16x16x32_bf16 v[96:99], v[152:155], v[184:187], v[96:99]
	v_mfma_f32_16x16x32_bf16 v[84:87], v[144:147], v[202:205], v[84:87]
	v_mfma_f32_16x16x32_bf16 v[80:83], v[152:155], v[202:205], v[80:83]
	v_mfma_f32_16x16x32_bf16 v[68:71], v[144:147], v[210:213], v[68:71]
	v_mfma_f32_16x16x32_bf16 v[64:67], v[152:155], v[210:213], v[64:67]
	v_mfma_f32_16x16x32_bf16 v[116:119], v[148:151], v[180:183], v[116:119]
	v_mfma_f32_16x16x32_bf16 v[112:115], v[156:159], v[180:183], v[112:115]
	v_mfma_f32_16x16x32_bf16 v[100:103], v[148:151], v[198:201], v[100:103]
	v_mfma_f32_16x16x32_bf16 v[96:99], v[156:159], v[198:201], v[96:99]
	v_mfma_f32_16x16x32_bf16 v[84:87], v[148:151], v[206:209], v[84:87]
	v_mfma_f32_16x16x32_bf16 v[80:83], v[156:159], v[206:209], v[80:83]
	v_mfma_f32_16x16x32_bf16 v[68:71], v[148:151], v[214:217], v[68:71]
	v_mfma_f32_16x16x32_bf16 v[64:67], v[156:159], v[214:217], v[64:67]
	s_barrier
	s_add_i32 s35, s35, s6
	v_lshl_add_u64 v[218:219], v[218:219], 0, s[16:17]
	s_mov_b32 m0, s35
	s_setprio 2
	ds_read_b128 v[176:179], v195 offset:49152
	ds_read_b128 v[180:183], v195 offset:50176
	ds_read_b128 v[184:187], v195 offset:51200
	ds_read_b128 v[198:201], v195 offset:52224
	ds_read_b128 v[202:205], v195 offset:53248
	ds_read_b128 v[206:209], v195 offset:54272
	ds_read_b128 v[210:213], v195 offset:55296
	ds_read_b128 v[214:217], v195 offset:56320
	s_setprio 0
	global_load_lds_dwordx4 v[218:219], off
	s_add_i32 m0, s35, 0x2000
	s_add_u32 s44, s44, 0x20080
	v_lshl_add_u64 v[218:219], v[220:221], 0, s[16:17]
	s_addc_u32 s45, s45, 0
	s_add_i32 s35, s39, s6
	global_load_lds_dwordx4 v[218:219], off
	v_lshl_add_u64 v[218:219], s[44:45], 0, v[162:163]
	s_mov_b32 m0, s35
	s_nop 0
	global_load_lds_dwordx4 v[218:219], off
	v_lshl_add_u64 v[218:219], s[44:45], 0, v[166:167]
	s_add_i32 m0, s35, 0x2000
	s_nop 0
	global_load_lds_dwordx4 v[218:219], off
	v_lshl_add_u64 v[218:219], v[222:223], 0, s[16:17]
	s_mov_b32 m0, s28
	s_nop 0
	global_load_lds_dwordx4 v[218:219], off
	v_lshl_add_u64 v[218:219], v[224:225], 0, s[16:17]
	s_mov_b32 m0, s29
	s_nop 0
	global_load_lds_dwordx4 v[218:219], off
	s_waitcnt vmcnt(8)
	s_waitcnt lgkmcnt(0)
	s_barrier
	s_waitcnt lgkmcnt(0)
	v_mfma_f32_16x16x32_bf16 v[60:63], v[128:131], v[176:179], v[60:63]
	v_mfma_f32_16x16x32_bf16 v[56:59], v[136:139], v[176:179], v[56:59]
	v_mfma_f32_16x16x32_bf16 v[44:47], v[128:131], v[184:187], v[44:47]
	v_mfma_f32_16x16x32_bf16 v[40:43], v[136:139], v[184:187], v[40:43]
	v_mfma_f32_16x16x32_bf16 v[28:31], v[128:131], v[202:205], v[28:31]
	v_mfma_f32_16x16x32_bf16 v[24:27], v[136:139], v[202:205], v[24:27]
	v_mfma_f32_16x16x32_bf16 v[12:15], v[128:131], v[210:213], v[12:15]
	v_mfma_f32_16x16x32_bf16 v[8:11], v[136:139], v[210:213], v[8:11]
	v_mfma_f32_16x16x32_bf16 v[60:63], v[132:135], v[180:183], v[60:63]
	v_mfma_f32_16x16x32_bf16 v[56:59], v[140:143], v[180:183], v[56:59]
	v_mfma_f32_16x16x32_bf16 v[44:47], v[132:135], v[198:201], v[44:47]
	v_mfma_f32_16x16x32_bf16 v[40:43], v[140:143], v[198:201], v[40:43]
	v_mfma_f32_16x16x32_bf16 v[28:31], v[132:135], v[206:209], v[28:31]
	v_mfma_f32_16x16x32_bf16 v[24:27], v[140:143], v[206:209], v[24:27]
	v_mfma_f32_16x16x32_bf16 v[12:15], v[132:135], v[214:217], v[12:15]
	v_mfma_f32_16x16x32_bf16 v[8:11], v[140:143], v[214:217], v[8:11]
	v_mfma_f32_16x16x32_bf16 v[52:55], v[144:147], v[176:179], v[52:55]
	v_mfma_f32_16x16x32_bf16 v[48:51], v[152:155], v[176:179], v[48:51]
	v_mfma_f32_16x16x32_bf16 v[36:39], v[144:147], v[184:187], v[36:39]
	v_mfma_f32_16x16x32_bf16 v[32:35], v[152:155], v[184:187], v[32:35]
	v_mfma_f32_16x16x32_bf16 v[20:23], v[144:147], v[202:205], v[20:23]
	v_mfma_f32_16x16x32_bf16 v[16:19], v[152:155], v[202:205], v[16:19]
	v_mfma_f32_16x16x32_bf16 v[4:7], v[144:147], v[210:213], v[4:7]
	v_mfma_f32_16x16x32_bf16 v[0:3], v[152:155], v[210:213], v[0:3]
	v_mfma_f32_16x16x32_bf16 v[52:55], v[148:151], v[180:183], v[52:55]
	v_mfma_f32_16x16x32_bf16 v[48:51], v[156:159], v[180:183], v[48:51]
	v_mfma_f32_16x16x32_bf16 v[36:39], v[148:151], v[198:201], v[36:39]
	v_mfma_f32_16x16x32_bf16 v[32:35], v[156:159], v[198:201], v[32:35]
	v_mfma_f32_16x16x32_bf16 v[20:23], v[148:151], v[206:209], v[20:23]
	v_mfma_f32_16x16x32_bf16 v[16:19], v[156:159], v[206:209], v[16:19]
	v_mfma_f32_16x16x32_bf16 v[4:7], v[148:151], v[214:217], v[4:7]
	v_mfma_f32_16x16x32_bf16 v[0:3], v[156:159], v[214:217], v[0:3]
	s_barrier
	s_add_i32 s31, s31, 2
	s_add_u32 s42, s42, 0x100
	s_addc_u32 s43, s43, 0
	s_add_u32 s11, s11, 0x100
	s_addc_u32 s23, s23, 0
	s_cmp_gt_u32 s31, 5
	s_cbranch_scc0 .LBB0_577
	s_and_b64 vcc, exec, s[18:19]
	s_cbranch_vccz .LBB0_580
	s_barrier

.LBB0_664:
	s_setprio 2
	ds_read_b128 v[156:159], v151
	ds_read_b128 v[160:163], v151 offset:1024
	ds_read_b128 v[164:167], v151 offset:2048
	ds_read_b128 v[168:171], v151 offset:3072
	ds_read_b128 v[172:175], v152
	ds_read_b128 v[176:179], v152 offset:1024
	ds_read_b128 v[180:183], v152 offset:2048
	ds_read_b128 v[184:187], v152 offset:3072
	s_add_u32 s22, s20, 0xfff80080
	s_addc_u32 s23, s21, -1
	s_cmp_eq_u32 s48, 28
	s_cselect_b32 s31, s13, s23
	s_cselect_b32 s30, s44, s22
	s_cselect_b32 s23, s15, s47
	s_cselect_b32 s22, s45, s46
	v_lshl_add_u64 v[146:147], s[20:21], 0, v[138:139]
	s_add_i32 m0, s11, 0xc000
	ds_read_b128 v[190:193], v153
	ds_read_b128 v[194:197], v153 offset:1024
	ds_read_b128 v[198:201], v153 offset:2048
	ds_read_b128 v[202:205], v153 offset:3072
	ds_read_b128 v[206:209], v153 offset:4096
	ds_read_b128 v[210:213], v153 offset:5120
	ds_read_b128 v[214:217], v153 offset:6144
	ds_read_b128 v[218:221], v153 offset:7168
	s_setprio 0
	global_load_lds_dwordx4 v[146:147], off
	v_lshl_add_u64 v[146:147], s[20:21], 0, v[140:141]
	s_add_i32 m0, s11, 0xe000
	s_nop 0
	global_load_lds_dwordx4 v[146:147], off
	s_waitcnt vmcnt(8)
	s_waitcnt lgkmcnt(0)
	s_barrier
	s_waitcnt lgkmcnt(0)
	v_mfma_f32_16x16x32_bf16 v[116:119], v[156:159], v[190:193], v[116:119]
	v_mfma_f32_16x16x32_bf16 v[112:115], v[164:167], v[190:193], v[112:115]
	v_mfma_f32_16x16x32_bf16 v[100:103], v[156:159], v[198:201], v[100:103]
	v_mfma_f32_16x16x32_bf16 v[96:99], v[164:167], v[198:201], v[96:99]
	v_mfma_f32_16x16x32_bf16 v[84:87], v[156:159], v[206:209], v[84:87]
	v_mfma_f32_16x16x32_bf16 v[80:83], v[164:167], v[206:209], v[80:83]
	v_mfma_f32_16x16x32_bf16 v[68:71], v[156:159], v[214:217], v[68:71]
	v_mfma_f32_16x16x32_bf16 v[64:67], v[164:167], v[214:217], v[64:67]
	v_mfma_f32_16x16x32_bf16 v[116:119], v[160:163], v[194:197], v[116:119]
	v_mfma_f32_16x16x32_bf16 v[112:115], v[168:171], v[194:197], v[112:115]
	v_mfma_f32_16x16x32_bf16 v[100:103], v[160:163], v[202:205], v[100:103]
	v_mfma_f32_16x16x32_bf16 v[96:99], v[168:171], v[202:205], v[96:99]
	v_mfma_f32_16x16x32_bf16 v[84:87], v[160:163], v[210:213], v[84:87]
	v_mfma_f32_16x16x32_bf16 v[80:83], v[168:171], v[210:213], v[80:83]
	v_mfma_f32_16x16x32_bf16 v[68:71], v[160:163], v[218:221], v[68:71]
	v_mfma_f32_16x16x32_bf16 v[64:67], v[168:171], v[218:221], v[64:67]
	v_mfma_f32_16x16x32_bf16 v[124:127], v[172:175], v[190:193], v[124:127]
	v_mfma_f32_16x16x32_bf16 v[120:123], v[180:183], v[190:193], v[120:123]
	v_mfma_f32_16x16x32_bf16 v[108:111], v[172:175], v[198:201], v[108:111]
	v_mfma_f32_16x16x32_bf16 v[104:107], v[180:183], v[198:201], v[104:107]
	v_mfma_f32_16x16x32_bf16 v[92:95], v[172:175], v[206:209], v[92:95]
	v_mfma_f32_16x16x32_bf16 v[88:91], v[180:183], v[206:209], v[88:91]
	v_mfma_f32_16x16x32_bf16 v[76:79], v[172:175], v[214:217], v[76:79]
	v_mfma_f32_16x16x32_bf16 v[72:75], v[180:183], v[214:217], v[72:75]
	v_mfma_f32_16x16x32_bf16 v[124:127], v[176:179], v[194:197], v[124:127]
	v_mfma_f32_16x16x32_bf16 v[120:123], v[184:187], v[194:197], v[120:123]
	v_mfma_f32_16x16x32_bf16 v[108:111], v[176:179], v[202:205], v[108:111]
	v_mfma_f32_16x16x32_bf16 v[104:107], v[184:187], v[202:205], v[104:107]
	v_mfma_f32_16x16x32_bf16 v[92:95], v[176:179], v[210:213], v[92:95]
	v_mfma_f32_16x16x32_bf16 v[88:91], v[184:187], v[210:213], v[88:91]
	v_mfma_f32_16x16x32_bf16 v[76:79], v[176:179], v[218:221], v[76:79]
	v_mfma_f32_16x16x32_bf16 v[72:75], v[184:187], v[218:221], v[72:75]
	s_barrier
	s_add_i32 s49, s40, s26
	v_lshl_add_u64 v[146:147], s[22:23], 0, v[130:131]
	s_mov_b32 m0, s49
	s_setprio 2
	ds_read_b128 v[190:193], v153 offset:16384
	ds_read_b128 v[194:197], v153 offset:17408
	ds_read_b128 v[198:201], v153 offset:18432
	ds_read_b128 v[202:205], v153 offset:19456
	ds_read_b128 v[206:209], v153 offset:20480
	ds_read_b128 v[210:213], v153 offset:21504
	ds_read_b128 v[214:217], v153 offset:22528
	ds_read_b128 v[218:221], v153 offset:23552
	s_setprio 0
	global_load_lds_dwordx4 v[146:147], off
	s_add_i32 m0, s49, 0x2000
	s_add_u32 s50, s22, 0x80000
	v_lshl_add_u64 v[222:223], s[22:23], 0, v[134:135]
	s_addc_u32 s51, s23, 0
	s_add_i32 s49, s41, s26
	global_load_lds_dwordx4 v[222:223], off
	v_lshl_add_u64 v[224:225], s[50:51], 0, v[130:131]
	s_mov_b32 m0, s49
	v_lshl_add_u64 v[226:227], s[30:31], 0, v[132:133]
	global_load_lds_dwordx4 v[224:225], off
	v_lshl_add_u64 v[224:225], s[50:51], 0, v[134:135]
	s_add_i32 m0, s49, 0x2000
	s_nop 0
	global_load_lds_dwordx4 v[224:225], off
	v_lshl_add_u64 v[224:225], s[30:31], 0, v[128:129]
	s_mov_b32 m0, s11
	s_nop 0
	global_load_lds_dwordx4 v[224:225], off
	s_mov_b32 m0, s28
	s_nop 0
	global_load_lds_dwordx4 v[226:227], off
	s_waitcnt vmcnt(8)
	s_waitcnt lgkmcnt(0)
	s_barrier
	s_waitcnt lgkmcnt(0)
	v_mfma_f32_16x16x32_bf16 v[52:55], v[156:159], v[190:193], v[52:55]
	v_mfma_f32_16x16x32_bf16 v[48:51], v[164:167], v[190:193], v[48:51]
	v_mfma_f32_16x16x32_bf16 v[36:39], v[156:159], v[198:201], v[36:39]
	v_mfma_f32_16x16x32_bf16 v[32:35], v[164:167], v[198:201], v[32:35]
	v_mfma_f32_16x16x32_bf16 v[20:23], v[156:159], v[206:209], v[20:23]
	v_mfma_f32_16x16x32_bf16 v[16:19], v[164:167], v[206:209], v[16:19]
	v_mfma_f32_16x16x32_bf16 v[8:11], v[156:159], v[214:217], v[8:11]
	v_mfma_f32_16x16x32_bf16 v[0:3], v[164:167], v[214:217], v[0:3]
	v_mfma_f32_16x16x32_bf16 v[52:55], v[160:163], v[194:197], v[52:55]
	v_mfma_f32_16x16x32_bf16 v[48:51], v[168:171], v[194:197], v[48:51]
	v_mfma_f32_16x16x32_bf16 v[36:39], v[160:163], v[202:205], v[36:39]
	v_mfma_f32_16x16x32_bf16 v[32:35], v[168:171], v[202:205], v[32:35]
	v_mfma_f32_16x16x32_bf16 v[20:23], v[160:163], v[210:213], v[20:23]
	v_mfma_f32_16x16x32_bf16 v[16:19], v[168:171], v[210:213], v[16:19]
	v_mfma_f32_16x16x32_bf16 v[8:11], v[160:163], v[218:221], v[8:11]
	v_mfma_f32_16x16x32_bf16 v[0:3], v[168:171], v[218:221], v[0:3]
	v_mfma_f32_16x16x32_bf16 v[60:63], v[172:175], v[190:193], v[60:63]
	v_mfma_f32_16x16x32_bf16 v[56:59], v[180:183], v[190:193], v[56:59]
	v_mfma_f32_16x16x32_bf16 v[44:47], v[172:175], v[198:201], v[44:47]
	v_mfma_f32_16x16x32_bf16 v[40:43], v[180:183], v[198:201], v[40:43]
	v_mfma_f32_16x16x32_bf16 v[28:31], v[172:175], v[206:209], v[28:31]
	v_mfma_f32_16x16x32_bf16 v[24:27], v[180:183], v[206:209], v[24:27]
	v_mfma_f32_16x16x32_bf16 v[12:15], v[172:175], v[214:217], v[12:15]
	v_mfma_f32_16x16x32_bf16 v[4:7], v[180:183], v[214:217], v[4:7]
	v_mfma_f32_16x16x32_bf16 v[60:63], v[176:179], v[194:197], v[60:63]
	v_mfma_f32_16x16x32_bf16 v[56:59], v[184:187], v[194:197], v[56:59]
	v_mfma_f32_16x16x32_bf16 v[44:47], v[176:179], v[202:205], v[44:47]
	v_mfma_f32_16x16x32_bf16 v[40:43], v[184:187], v[202:205], v[40:43]
	v_mfma_f32_16x16x32_bf16 v[28:31], v[176:179], v[210:213], v[28:31]
	v_mfma_f32_16x16x32_bf16 v[24:27], v[184:187], v[210:213], v[24:27]
	v_mfma_f32_16x16x32_bf16 v[12:15], v[176:179], v[218:221], v[12:15]
	v_mfma_f32_16x16x32_bf16 v[4:7], v[184:187], v[218:221], v[4:7]
	s_barrier
	s_add_i32 s49, 0, 0x18000
	s_add_i32 s50, 0, 0x1c000
	v_add_u32_e32 v168, s49, v149
	v_add_u32_e32 v184, s50, v149
	s_setprio 2
	ds_read_b128 v[156:159], v168
	ds_read_b128 v[160:163], v168 offset:1024
	ds_read_b128 v[164:167], v168 offset:2048
	ds_read_b128 v[168:171], v168 offset:3072
	ds_read_b128 v[172:175], v184
	ds_read_b128 v[176:179], v184 offset:1024
	ds_read_b128 v[180:183], v184 offset:2048
	ds_read_b128 v[184:187], v184 offset:3072
	s_add_u32 s30, s30, 0x80000
	s_addc_u32 s31, s31, 0
	s_mov_b32 m0, s29
	v_lshl_add_u64 v[228:229], s[30:31], 0, v[128:129]
	ds_read_b128 v[190:193], v153 offset:32768
	ds_read_b128 v[194:197], v153 offset:33792
	ds_read_b128 v[198:201], v153 offset:34816
	ds_read_b128 v[202:205], v153 offset:35840
	ds_read_b128 v[206:209], v153 offset:36864
	ds_read_b128 v[210:213], v153 offset:37888
	ds_read_b128 v[214:217], v153 offset:38912
	ds_read_b128 v[218:221], v153 offset:39936
	s_setprio 0
	global_load_lds_dwordx4 v[228:229], off
	v_lshl_add_u64 v[228:229], s[30:31], 0, v[132:133]
	s_mov_b32 m0, s33
	s_nop 0
	global_load_lds_dwordx4 v[228:229], off
	s_waitcnt vmcnt(8)
	s_waitcnt lgkmcnt(0)
	s_barrier
	s_waitcnt lgkmcnt(0)
	v_mfma_f32_16x16x32_bf16 v[116:119], v[156:159], v[190:193], v[116:119]
	v_mfma_f32_16x16x32_bf16 v[112:115], v[164:167], v[190:193], v[112:115]
	v_mfma_f32_16x16x32_bf16 v[100:103], v[156:159], v[198:201], v[100:103]
	v_mfma_f32_16x16x32_bf16 v[96:99], v[164:167], v[198:201], v[96:99]
	v_mfma_f32_16x16x32_bf16 v[84:87], v[156:159], v[206:209], v[84:87]
	v_mfma_f32_16x16x32_bf16 v[80:83], v[164:167], v[206:209], v[80:83]
	v_mfma_f32_16x16x32_bf16 v[68:71], v[156:159], v[214:217], v[68:71]
	v_mfma_f32_16x16x32_bf16 v[64:67], v[164:167], v[214:217], v[64:67]
	v_mfma_f32_16x16x32_bf16 v[116:119], v[160:163], v[194:197], v[116:119]
	v_mfma_f32_16x16x32_bf16 v[112:115], v[168:171], v[194:197], v[112:115]
	v_mfma_f32_16x16x32_bf16 v[100:103], v[160:163], v[202:205], v[100:103]
	v_mfma_f32_16x16x32_bf16 v[96:99], v[168:171], v[202:205], v[96:99]
	v_mfma_f32_16x16x32_bf16 v[84:87], v[160:163], v[210:213], v[84:87]
	v_mfma_f32_16x16x32_bf16 v[80:83], v[168:171], v[210:213], v[80:83]
	v_mfma_f32_16x16x32_bf16 v[68:71], v[160:163], v[218:221], v[68:71]
	v_mfma_f32_16x16x32_bf16 v[64:67], v[168:171], v[218:221], v[64:67]
	v_mfma_f32_16x16x32_bf16 v[124:127], v[172:175], v[190:193], v[124:127]
	v_mfma_f32_16x16x32_bf16 v[120:123], v[180:183], v[190:193], v[120:123]
	v_mfma_f32_16x16x32_bf16 v[108:111], v[172:175], v[198:201], v[108:111]
	v_mfma_f32_16x16x32_bf16 v[104:107], v[180:183], v[198:201], v[104:107]
	v_mfma_f32_16x16x32_bf16 v[92:95], v[172:175], v[206:209], v[92:95]
	v_mfma_f32_16x16x32_bf16 v[88:91], v[180:183], v[206:209], v[88:91]
	v_mfma_f32_16x16x32_bf16 v[76:79], v[172:175], v[214:217], v[76:79]
	v_mfma_f32_16x16x32_bf16 v[72:75], v[180:183], v[214:217], v[72:75]
	v_mfma_f32_16x16x32_bf16 v[124:127], v[176:179], v[194:197], v[124:127]
	v_mfma_f32_16x16x32_bf16 v[120:123], v[184:187], v[194:197], v[120:123]
	v_mfma_f32_16x16x32_bf16 v[108:111], v[176:179], v[202:205], v[108:111]
	v_mfma_f32_16x16x32_bf16 v[104:107], v[184:187], v[202:205], v[104:107]
	v_mfma_f32_16x16x32_bf16 v[92:95], v[176:179], v[210:213], v[92:95]
	v_mfma_f32_16x16x32_bf16 v[88:91], v[184:187], v[210:213], v[88:91]
	v_mfma_f32_16x16x32_bf16 v[76:79], v[176:179], v[218:221], v[76:79]
	v_mfma_f32_16x16x32_bf16 v[72:75], v[184:187], v[218:221], v[72:75]
	s_barrier
	s_add_i32 s30, s49, s26
	v_lshl_add_u64 v[146:147], v[146:147], 0, s[6:7]
	s_mov_b32 m0, s30
	s_setprio 2
	ds_read_b128 v[190:193], v153 offset:49152
	ds_read_b128 v[194:197], v153 offset:50176
	ds_read_b128 v[198:201], v153 offset:51200
	ds_read_b128 v[202:205], v153 offset:52224
	ds_read_b128 v[206:209], v153 offset:53248
	ds_read_b128 v[210:213], v153 offset:54272
	ds_read_b128 v[214:217], v153 offset:55296
	ds_read_b128 v[218:221], v153 offset:56320
	s_setprio 0
	global_load_lds_dwordx4 v[146:147], off
	s_add_i32 m0, s30, 0x2000
	s_add_u32 s22, s22, 0x80080
	v_lshl_add_u64 v[146:147], v[222:223], 0, s[6:7]
	s_addc_u32 s23, s23, 0
	s_add_i32 s30, s50, s26
	global_load_lds_dwordx4 v[146:147], off
	v_lshl_add_u64 v[146:147], s[22:23], 0, v[130:131]
	s_mov_b32 m0, s30
	s_nop 0
	global_load_lds_dwordx4 v[146:147], off
	v_lshl_add_u64 v[146:147], s[22:23], 0, v[134:135]
	s_add_i32 m0, s30, 0x2000
	s_nop 0
	global_load_lds_dwordx4 v[146:147], off
	v_lshl_add_u64 v[146:147], v[224:225], 0, s[6:7]
	s_mov_b32 m0, s37
	s_nop 0
	global_load_lds_dwordx4 v[146:147], off
	v_lshl_add_u64 v[146:147], v[226:227], 0, s[6:7]
	s_mov_b32 m0, s38
	s_nop 0
	global_load_lds_dwordx4 v[146:147], off
	s_waitcnt vmcnt(8)
	s_waitcnt lgkmcnt(0)
	s_barrier
	s_waitcnt lgkmcnt(0)
	v_mfma_f32_16x16x32_bf16 v[52:55], v[156:159], v[190:193], v[52:55]
	v_mfma_f32_16x16x32_bf16 v[48:51], v[164:167], v[190:193], v[48:51]
	v_mfma_f32_16x16x32_bf16 v[36:39], v[156:159], v[198:201], v[36:39]
	v_mfma_f32_16x16x32_bf16 v[32:35], v[164:167], v[198:201], v[32:35]
	v_mfma_f32_16x16x32_bf16 v[20:23], v[156:159], v[206:209], v[20:23]
	v_mfma_f32_16x16x32_bf16 v[16:19], v[164:167], v[206:209], v[16:19]
	v_mfma_f32_16x16x32_bf16 v[8:11], v[156:159], v[214:217], v[8:11]
	v_mfma_f32_16x16x32_bf16 v[0:3], v[164:167], v[214:217], v[0:3]
	v_mfma_f32_16x16x32_bf16 v[52:55], v[160:163], v[194:197], v[52:55]
	v_mfma_f32_16x16x32_bf16 v[48:51], v[168:171], v[194:197], v[48:51]
	v_mfma_f32_16x16x32_bf16 v[36:39], v[160:163], v[202:205], v[36:39]
	v_mfma_f32_16x16x32_bf16 v[32:35], v[168:171], v[202:205], v[32:35]
	v_mfma_f32_16x16x32_bf16 v[20:23], v[160:163], v[210:213], v[20:23]
	v_mfma_f32_16x16x32_bf16 v[16:19], v[168:171], v[210:213], v[16:19]
	v_mfma_f32_16x16x32_bf16 v[8:11], v[160:163], v[218:221], v[8:11]
	v_mfma_f32_16x16x32_bf16 v[0:3], v[168:171], v[218:221], v[0:3]
	v_mfma_f32_16x16x32_bf16 v[60:63], v[172:175], v[190:193], v[60:63]
	v_mfma_f32_16x16x32_bf16 v[56:59], v[180:183], v[190:193], v[56:59]
	v_mfma_f32_16x16x32_bf16 v[44:47], v[172:175], v[198:201], v[44:47]
	v_mfma_f32_16x16x32_bf16 v[40:43], v[180:183], v[198:201], v[40:43]
	v_mfma_f32_16x16x32_bf16 v[28:31], v[172:175], v[206:209], v[28:31]
	v_mfma_f32_16x16x32_bf16 v[24:27], v[180:183], v[206:209], v[24:27]
	v_mfma_f32_16x16x32_bf16 v[12:15], v[172:175], v[214:217], v[12:15]
	v_mfma_f32_16x16x32_bf16 v[4:7], v[180:183], v[214:217], v[4:7]
	v_mfma_f32_16x16x32_bf16 v[60:63], v[176:179], v[194:197], v[60:63]
	v_mfma_f32_16x16x32_bf16 v[56:59], v[184:187], v[194:197], v[56:59]
	v_mfma_f32_16x16x32_bf16 v[44:47], v[176:179], v[202:205], v[44:47]
	v_mfma_f32_16x16x32_bf16 v[40:43], v[184:187], v[202:205], v[40:43]
	v_mfma_f32_16x16x32_bf16 v[28:31], v[176:179], v[210:213], v[28:31]
	v_mfma_f32_16x16x32_bf16 v[24:27], v[184:187], v[210:213], v[24:27]
	v_mfma_f32_16x16x32_bf16 v[12:15], v[176:179], v[218:221], v[12:15]
	v_mfma_f32_16x16x32_bf16 v[4:7], v[184:187], v[218:221], v[4:7]
	s_barrier
	s_add_i32 s48, s48, 2
	s_add_u32 s20, s20, 0x100
	s_addc_u32 s21, s21, 0
	s_add_u32 s46, s46, 0x100
	s_addc_u32 s47, s47, 0
	s_cmp_gt_u32 s48, 29
	s_cbranch_scc0 .LBB0_664
	s_and_b64 vcc, exec, s[8:9]
	s_cbranch_vccz .LBB0_667
	s_barrier

.LBB0_749:
	s_setprio 2
	ds_read_b128 v[128:131], v179
	ds_read_b128 v[132:135], v179 offset:1024
	ds_read_b128 v[136:139], v179 offset:2048
	ds_read_b128 v[140:143], v179 offset:3072
	ds_read_b128 v[160:163], v180
	ds_read_b128 v[164:167], v180 offset:1024
	ds_read_b128 v[168:171], v180 offset:2048
	ds_read_b128 v[172:175], v180 offset:3072
	s_add_u32 s20, s10, 0xffea0080
	s_addc_u32 s21, s11, -1
	s_cmpk_eq_i32 s48, 0x54
	s_cselect_b32 s23, s1, s21
	s_cselect_b32 s22, s0, s20
	s_cselect_b32 s21, s19, s47
	s_cselect_b32 s20, s18, s46
	v_lshl_add_u64 v[218:219], s[10:11], 0, v[152:153]
	s_add_i32 m0, s27, 0xc000
	ds_read_b128 v[184:187], v181
	ds_read_b128 v[190:193], v181 offset:1024
	ds_read_b128 v[194:197], v181 offset:2048
	ds_read_b128 v[198:201], v181 offset:3072
	ds_read_b128 v[202:205], v181 offset:4096
	ds_read_b128 v[206:209], v181 offset:5120
	ds_read_b128 v[210:213], v181 offset:6144
	ds_read_b128 v[214:217], v181 offset:7168
	s_setprio 0
	global_load_lds_dwordx4 v[218:219], off
	v_lshl_add_u64 v[218:219], s[10:11], 0, v[154:155]
	s_add_i32 m0, s27, 0xe000
	s_nop 0
	global_load_lds_dwordx4 v[218:219], off
	s_waitcnt vmcnt(8)
	s_waitcnt lgkmcnt(0)
	s_barrier
	s_waitcnt lgkmcnt(0)
	v_mfma_f32_16x16x32_bf16 v[124:127], v[128:131], v[184:187], v[124:127]
	v_mfma_f32_16x16x32_bf16 v[120:123], v[136:139], v[184:187], v[120:123]
	v_mfma_f32_16x16x32_bf16 v[108:111], v[128:131], v[194:197], v[108:111]
	v_mfma_f32_16x16x32_bf16 v[104:107], v[136:139], v[194:197], v[104:107]
	v_mfma_f32_16x16x32_bf16 v[92:95], v[128:131], v[202:205], v[92:95]
	v_mfma_f32_16x16x32_bf16 v[88:91], v[136:139], v[202:205], v[88:91]
	v_mfma_f32_16x16x32_bf16 v[76:79], v[128:131], v[210:213], v[76:79]
	v_mfma_f32_16x16x32_bf16 v[72:75], v[136:139], v[210:213], v[72:75]
	v_mfma_f32_16x16x32_bf16 v[124:127], v[132:135], v[190:193], v[124:127]
	v_mfma_f32_16x16x32_bf16 v[120:123], v[140:143], v[190:193], v[120:123]
	v_mfma_f32_16x16x32_bf16 v[108:111], v[132:135], v[198:201], v[108:111]
	v_mfma_f32_16x16x32_bf16 v[104:107], v[140:143], v[198:201], v[104:107]
	v_mfma_f32_16x16x32_bf16 v[92:95], v[132:135], v[206:209], v[92:95]
	v_mfma_f32_16x16x32_bf16 v[88:91], v[140:143], v[206:209], v[88:91]
	v_mfma_f32_16x16x32_bf16 v[76:79], v[132:135], v[214:217], v[76:79]
	v_mfma_f32_16x16x32_bf16 v[72:75], v[140:143], v[214:217], v[72:75]
	v_mfma_f32_16x16x32_bf16 v[116:119], v[160:163], v[184:187], v[116:119]
	v_mfma_f32_16x16x32_bf16 v[112:115], v[168:171], v[184:187], v[112:115]
	v_mfma_f32_16x16x32_bf16 v[100:103], v[160:163], v[194:197], v[100:103]
	v_mfma_f32_16x16x32_bf16 v[96:99], v[168:171], v[194:197], v[96:99]
	v_mfma_f32_16x16x32_bf16 v[84:87], v[160:163], v[202:205], v[84:87]
	v_mfma_f32_16x16x32_bf16 v[80:83], v[168:171], v[202:205], v[80:83]
	v_mfma_f32_16x16x32_bf16 v[68:71], v[160:163], v[210:213], v[68:71]
	v_mfma_f32_16x16x32_bf16 v[64:67], v[168:171], v[210:213], v[64:67]
	v_mfma_f32_16x16x32_bf16 v[116:119], v[164:167], v[190:193], v[116:119]
	v_mfma_f32_16x16x32_bf16 v[112:115], v[172:175], v[190:193], v[112:115]
	v_mfma_f32_16x16x32_bf16 v[100:103], v[164:167], v[198:201], v[100:103]
	v_mfma_f32_16x16x32_bf16 v[96:99], v[172:175], v[198:201], v[96:99]
	v_mfma_f32_16x16x32_bf16 v[84:87], v[164:167], v[206:209], v[84:87]
	v_mfma_f32_16x16x32_bf16 v[80:83], v[172:175], v[206:209], v[80:83]
	v_mfma_f32_16x16x32_bf16 v[68:71], v[164:167], v[214:217], v[68:71]
	v_mfma_f32_16x16x32_bf16 v[64:67], v[172:175], v[214:217], v[64:67]
	s_barrier
	s_add_i32 s49, s39, s26
	v_lshl_add_u64 v[218:219], s[20:21], 0, v[146:147]
	s_mov_b32 m0, s49
	s_setprio 2
	ds_read_b128 v[184:187], v181 offset:16384
	ds_read_b128 v[190:193], v181 offset:17408
	ds_read_b128 v[194:197], v181 offset:18432
	ds_read_b128 v[198:201], v181 offset:19456
	ds_read_b128 v[202:205], v181 offset:20480
	ds_read_b128 v[206:209], v181 offset:21504
	ds_read_b128 v[210:213], v181 offset:22528
	ds_read_b128 v[214:217], v181 offset:23552
	s_setprio 0
	global_load_lds_dwordx4 v[218:219], off
	s_add_i32 m0, s49, 0x2000
	s_add_u32 s50, s20, 0x160000
	v_lshl_add_u64 v[220:221], s[20:21], 0, v[150:151]
	s_addc_u32 s51, s21, 0
	s_add_i32 s49, s40, s26
	global_load_lds_dwordx4 v[220:221], off
	v_lshl_add_u64 v[222:223], s[50:51], 0, v[146:147]
	s_mov_b32 m0, s49
	v_lshl_add_u64 v[224:225], s[22:23], 0, v[148:149]
	global_load_lds_dwordx4 v[222:223], off
	v_lshl_add_u64 v[222:223], s[50:51], 0, v[150:151]
	s_add_i32 m0, s49, 0x2000
	s_nop 0
	global_load_lds_dwordx4 v[222:223], off
	v_lshl_add_u64 v[222:223], s[22:23], 0, v[144:145]
	s_mov_b32 m0, s27
	s_nop 0
	global_load_lds_dwordx4 v[222:223], off
	s_mov_b32 m0, s28
	s_nop 0
	global_load_lds_dwordx4 v[224:225], off
	s_waitcnt vmcnt(8)
	s_waitcnt lgkmcnt(0)
	s_barrier
	s_waitcnt lgkmcnt(0)
	v_mfma_f32_16x16x32_bf16 v[60:63], v[128:131], v[184:187], v[60:63]
	v_mfma_f32_16x16x32_bf16 v[56:59], v[136:139], v[184:187], v[56:59]
	v_mfma_f32_16x16x32_bf16 v[44:47], v[128:131], v[194:197], v[44:47]
	v_mfma_f32_16x16x32_bf16 v[40:43], v[136:139], v[194:197], v[40:43]
	v_mfma_f32_16x16x32_bf16 v[28:31], v[128:131], v[202:205], v[28:31]
	v_mfma_f32_16x16x32_bf16 v[24:27], v[136:139], v[202:205], v[24:27]
	v_mfma_f32_16x16x32_bf16 v[12:15], v[128:131], v[210:213], v[12:15]
	v_mfma_f32_16x16x32_bf16 v[8:11], v[136:139], v[210:213], v[8:11]
	v_mfma_f32_16x16x32_bf16 v[60:63], v[132:135], v[190:193], v[60:63]
	v_mfma_f32_16x16x32_bf16 v[56:59], v[140:143], v[190:193], v[56:59]
	v_mfma_f32_16x16x32_bf16 v[44:47], v[132:135], v[198:201], v[44:47]
	v_mfma_f32_16x16x32_bf16 v[40:43], v[140:143], v[198:201], v[40:43]
	v_mfma_f32_16x16x32_bf16 v[28:31], v[132:135], v[206:209], v[28:31]
	v_mfma_f32_16x16x32_bf16 v[24:27], v[140:143], v[206:209], v[24:27]
	v_mfma_f32_16x16x32_bf16 v[12:15], v[132:135], v[214:217], v[12:15]
	v_mfma_f32_16x16x32_bf16 v[8:11], v[140:143], v[214:217], v[8:11]
	v_mfma_f32_16x16x32_bf16 v[52:55], v[160:163], v[184:187], v[52:55]
	v_mfma_f32_16x16x32_bf16 v[48:51], v[168:171], v[184:187], v[48:51]
	v_mfma_f32_16x16x32_bf16 v[36:39], v[160:163], v[194:197], v[36:39]
	v_mfma_f32_16x16x32_bf16 v[32:35], v[168:171], v[194:197], v[32:35]
	v_mfma_f32_16x16x32_bf16 v[20:23], v[160:163], v[202:205], v[20:23]
	v_mfma_f32_16x16x32_bf16 v[16:19], v[168:171], v[202:205], v[16:19]
	v_mfma_f32_16x16x32_bf16 v[4:7], v[160:163], v[210:213], v[4:7]
	v_mfma_f32_16x16x32_bf16 v[0:3], v[168:171], v[210:213], v[0:3]
	v_mfma_f32_16x16x32_bf16 v[52:55], v[164:167], v[190:193], v[52:55]
	v_mfma_f32_16x16x32_bf16 v[48:51], v[172:175], v[190:193], v[48:51]
	v_mfma_f32_16x16x32_bf16 v[36:39], v[164:167], v[198:201], v[36:39]
	v_mfma_f32_16x16x32_bf16 v[32:35], v[172:175], v[198:201], v[32:35]
	v_mfma_f32_16x16x32_bf16 v[20:23], v[164:167], v[206:209], v[20:23]
	v_mfma_f32_16x16x32_bf16 v[16:19], v[172:175], v[206:209], v[16:19]
	v_mfma_f32_16x16x32_bf16 v[4:7], v[164:167], v[214:217], v[4:7]
	v_mfma_f32_16x16x32_bf16 v[0:3], v[172:175], v[214:217], v[0:3]
	s_barrier
	s_add_i32 s49, 0, 0x18000
	s_add_i32 s50, 0, 0x1c000
	v_add_u32_e32 v140, s49, v177
	v_add_u32_e32 v172, s50, v177
	s_setprio 2
	ds_read_b128 v[128:131], v140
	ds_read_b128 v[132:135], v140 offset:1024
	ds_read_b128 v[136:139], v140 offset:2048
	ds_read_b128 v[140:143], v140 offset:3072
	ds_read_b128 v[160:163], v172
	ds_read_b128 v[164:167], v172 offset:1024
	ds_read_b128 v[168:171], v172 offset:2048
	ds_read_b128 v[172:175], v172 offset:3072
	s_add_u32 s22, s22, 0x160000
	s_addc_u32 s23, s23, 0
	s_mov_b32 m0, s29
	v_lshl_add_u64 v[226:227], s[22:23], 0, v[144:145]
	ds_read_b128 v[184:187], v181 offset:32768
	ds_read_b128 v[190:193], v181 offset:33792
	ds_read_b128 v[194:197], v181 offset:34816
	ds_read_b128 v[198:201], v181 offset:35840
	ds_read_b128 v[202:205], v181 offset:36864
	ds_read_b128 v[206:209], v181 offset:37888
	ds_read_b128 v[210:213], v181 offset:38912
	ds_read_b128 v[214:217], v181 offset:39936
	s_setprio 0
	global_load_lds_dwordx4 v[226:227], off
	v_lshl_add_u64 v[226:227], s[22:23], 0, v[148:149]
	s_mov_b32 m0, s30
	s_nop 0
	global_load_lds_dwordx4 v[226:227], off
	s_waitcnt vmcnt(8)
	s_waitcnt lgkmcnt(0)
	s_barrier
	s_waitcnt lgkmcnt(0)
	v_mfma_f32_16x16x32_bf16 v[124:127], v[128:131], v[184:187], v[124:127]
	v_mfma_f32_16x16x32_bf16 v[120:123], v[136:139], v[184:187], v[120:123]
	v_mfma_f32_16x16x32_bf16 v[108:111], v[128:131], v[194:197], v[108:111]
	v_mfma_f32_16x16x32_bf16 v[104:107], v[136:139], v[194:197], v[104:107]
	v_mfma_f32_16x16x32_bf16 v[92:95], v[128:131], v[202:205], v[92:95]
	v_mfma_f32_16x16x32_bf16 v[88:91], v[136:139], v[202:205], v[88:91]
	v_mfma_f32_16x16x32_bf16 v[76:79], v[128:131], v[210:213], v[76:79]
	v_mfma_f32_16x16x32_bf16 v[72:75], v[136:139], v[210:213], v[72:75]
	v_mfma_f32_16x16x32_bf16 v[124:127], v[132:135], v[190:193], v[124:127]
	v_mfma_f32_16x16x32_bf16 v[120:123], v[140:143], v[190:193], v[120:123]
	v_mfma_f32_16x16x32_bf16 v[108:111], v[132:135], v[198:201], v[108:111]
	v_mfma_f32_16x16x32_bf16 v[104:107], v[140:143], v[198:201], v[104:107]
	v_mfma_f32_16x16x32_bf16 v[92:95], v[132:135], v[206:209], v[92:95]
	v_mfma_f32_16x16x32_bf16 v[88:91], v[140:143], v[206:209], v[88:91]
	v_mfma_f32_16x16x32_bf16 v[76:79], v[132:135], v[214:217], v[76:79]
	v_mfma_f32_16x16x32_bf16 v[72:75], v[140:143], v[214:217], v[72:75]
	v_mfma_f32_16x16x32_bf16 v[116:119], v[160:163], v[184:187], v[116:119]
	v_mfma_f32_16x16x32_bf16 v[112:115], v[168:171], v[184:187], v[112:115]
	v_mfma_f32_16x16x32_bf16 v[100:103], v[160:163], v[194:197], v[100:103]
	v_mfma_f32_16x16x32_bf16 v[96:99], v[168:171], v[194:197], v[96:99]
	v_mfma_f32_16x16x32_bf16 v[84:87], v[160:163], v[202:205], v[84:87]
	v_mfma_f32_16x16x32_bf16 v[80:83], v[168:171], v[202:205], v[80:83]
	v_mfma_f32_16x16x32_bf16 v[68:71], v[160:163], v[210:213], v[68:71]
	v_mfma_f32_16x16x32_bf16 v[64:67], v[168:171], v[210:213], v[64:67]
	v_mfma_f32_16x16x32_bf16 v[116:119], v[164:167], v[190:193], v[116:119]
	v_mfma_f32_16x16x32_bf16 v[112:115], v[172:175], v[190:193], v[112:115]
	v_mfma_f32_16x16x32_bf16 v[100:103], v[164:167], v[198:201], v[100:103]
	v_mfma_f32_16x16x32_bf16 v[96:99], v[172:175], v[198:201], v[96:99]
	v_mfma_f32_16x16x32_bf16 v[84:87], v[164:167], v[206:209], v[84:87]
	v_mfma_f32_16x16x32_bf16 v[80:83], v[172:175], v[206:209], v[80:83]
	v_mfma_f32_16x16x32_bf16 v[68:71], v[164:167], v[214:217], v[68:71]
	v_mfma_f32_16x16x32_bf16 v[64:67], v[172:175], v[214:217], v[64:67]
	s_barrier
	s_add_i32 s22, s49, s26
	v_lshl_add_u64 v[218:219], v[218:219], 0, s[12:13]
	s_mov_b32 m0, s22
	s_setprio 2
	ds_read_b128 v[184:187], v181 offset:49152
	ds_read_b128 v[190:193], v181 offset:50176
	ds_read_b128 v[194:197], v181 offset:51200
	ds_read_b128 v[198:201], v181 offset:52224
	ds_read_b128 v[202:205], v181 offset:53248
	ds_read_b128 v[206:209], v181 offset:54272
	ds_read_b128 v[210:213], v181 offset:55296
	ds_read_b128 v[214:217], v181 offset:56320
	s_setprio 0
	global_load_lds_dwordx4 v[218:219], off
	s_add_i32 m0, s22, 0x2000
	s_add_u32 s20, s20, 0x160080
	v_lshl_add_u64 v[218:219], v[220:221], 0, s[12:13]
	s_addc_u32 s21, s21, 0
	s_add_i32 s22, s50, s26
	global_load_lds_dwordx4 v[218:219], off
	v_lshl_add_u64 v[218:219], s[20:21], 0, v[146:147]
	s_mov_b32 m0, s22
	s_nop 0
	global_load_lds_dwordx4 v[218:219], off
	v_lshl_add_u64 v[218:219], s[20:21], 0, v[150:151]
	s_add_i32 m0, s22, 0x2000
	s_nop 0
	global_load_lds_dwordx4 v[218:219], off
	v_lshl_add_u64 v[218:219], v[222:223], 0, s[12:13]
	s_mov_b32 m0, s35
	s_nop 0
	global_load_lds_dwordx4 v[218:219], off
	v_lshl_add_u64 v[218:219], v[224:225], 0, s[12:13]
	s_mov_b32 m0, s36
	s_nop 0
	global_load_lds_dwordx4 v[218:219], off
	s_waitcnt vmcnt(8)
	s_waitcnt lgkmcnt(0)
	s_barrier
	s_waitcnt lgkmcnt(0)
	v_mfma_f32_16x16x32_bf16 v[60:63], v[128:131], v[184:187], v[60:63]
	v_mfma_f32_16x16x32_bf16 v[56:59], v[136:139], v[184:187], v[56:59]
	v_mfma_f32_16x16x32_bf16 v[44:47], v[128:131], v[194:197], v[44:47]
	v_mfma_f32_16x16x32_bf16 v[40:43], v[136:139], v[194:197], v[40:43]
	v_mfma_f32_16x16x32_bf16 v[28:31], v[128:131], v[202:205], v[28:31]
	v_mfma_f32_16x16x32_bf16 v[24:27], v[136:139], v[202:205], v[24:27]
	v_mfma_f32_16x16x32_bf16 v[12:15], v[128:131], v[210:213], v[12:15]
	v_mfma_f32_16x16x32_bf16 v[8:11], v[136:139], v[210:213], v[8:11]
	v_mfma_f32_16x16x32_bf16 v[60:63], v[132:135], v[190:193], v[60:63]
	v_mfma_f32_16x16x32_bf16 v[56:59], v[140:143], v[190:193], v[56:59]
	v_mfma_f32_16x16x32_bf16 v[44:47], v[132:135], v[198:201], v[44:47]
	v_mfma_f32_16x16x32_bf16 v[40:43], v[140:143], v[198:201], v[40:43]
	v_mfma_f32_16x16x32_bf16 v[28:31], v[132:135], v[206:209], v[28:31]
	v_mfma_f32_16x16x32_bf16 v[24:27], v[140:143], v[206:209], v[24:27]
	v_mfma_f32_16x16x32_bf16 v[12:15], v[132:135], v[214:217], v[12:15]
	v_mfma_f32_16x16x32_bf16 v[8:11], v[140:143], v[214:217], v[8:11]
	v_mfma_f32_16x16x32_bf16 v[52:55], v[160:163], v[184:187], v[52:55]
	v_mfma_f32_16x16x32_bf16 v[48:51], v[168:171], v[184:187], v[48:51]
	v_mfma_f32_16x16x32_bf16 v[36:39], v[160:163], v[194:197], v[36:39]
	v_mfma_f32_16x16x32_bf16 v[32:35], v[168:171], v[194:197], v[32:35]
	v_mfma_f32_16x16x32_bf16 v[20:23], v[160:163], v[202:205], v[20:23]
	v_mfma_f32_16x16x32_bf16 v[16:19], v[168:171], v[202:205], v[16:19]
	v_mfma_f32_16x16x32_bf16 v[4:7], v[160:163], v[210:213], v[4:7]
	v_mfma_f32_16x16x32_bf16 v[0:3], v[168:171], v[210:213], v[0:3]
	v_mfma_f32_16x16x32_bf16 v[52:55], v[164:167], v[190:193], v[52:55]
	v_mfma_f32_16x16x32_bf16 v[48:51], v[172:175], v[190:193], v[48:51]
	v_mfma_f32_16x16x32_bf16 v[36:39], v[164:167], v[198:201], v[36:39]
	v_mfma_f32_16x16x32_bf16 v[32:35], v[172:175], v[198:201], v[32:35]
	v_mfma_f32_16x16x32_bf16 v[20:23], v[164:167], v[206:209], v[20:23]
	v_mfma_f32_16x16x32_bf16 v[16:19], v[172:175], v[206:209], v[16:19]
	v_mfma_f32_16x16x32_bf16 v[4:7], v[164:167], v[214:217], v[4:7]
	v_mfma_f32_16x16x32_bf16 v[0:3], v[172:175], v[214:217], v[0:3]
	s_barrier
	s_add_i32 s48, s48, 2
	s_add_u32 s10, s10, 0x100
	s_addc_u32 s11, s11, 0
	s_add_u32 s46, s46, 0x100
	s_addc_u32 s47, s47, 0
	s_cmpk_gt_u32 s48, 0x55
	s_cbranch_scc0 .LBB0_749
	s_and_b64 vcc, exec, s[14:15]
	s_cbranch_vccz .LBB0_752
	s_barrier

.LBB0_838:
	s_setprio 2
	ds_read_b128 v[154:157], v143
	ds_read_b128 v[164:167], v143 offset:1024
	ds_read_b128 v[168:171], v143 offset:2048
	ds_read_b128 v[172:175], v143 offset:3072
	ds_read_b128 v[176:179], v160
	ds_read_b128 v[180:183], v160 offset:1024
	ds_read_b128 v[184:187], v160 offset:2048
	ds_read_b128 v[190:193], v160 offset:3072
	s_add_u32 s44, s10, 0xfff80080
	s_addc_u32 s45, s11, -1
	s_cmp_eq_u32 s62, 28
	s_cselect_b32 s47, s7, s45
	s_cselect_b32 s46, s35, s44
	s_cselect_b32 s45, s37, s61
	s_cselect_b32 s44, s59, s60
	v_lshl_add_u64 v[226:227], s[10:11], 0, v[146:147]
	s_add_i32 m0, s27, 0xc000
	ds_read_b128 v[194:197], v161
	ds_read_b128 v[198:201], v161 offset:1024
	ds_read_b128 v[202:205], v161 offset:2048
	ds_read_b128 v[206:209], v161 offset:3072
	ds_read_b128 v[210:213], v161 offset:4096
	ds_read_b128 v[214:217], v161 offset:5120
	ds_read_b128 v[218:221], v161 offset:6144
	ds_read_b128 v[222:225], v161 offset:7168
	s_setprio 0
	global_load_lds_dwordx4 v[226:227], off
	v_lshl_add_u64 v[226:227], s[10:11], 0, v[148:149]
	s_add_i32 m0, s27, 0xe000
	s_nop 0
	global_load_lds_dwordx4 v[226:227], off
	s_waitcnt vmcnt(8)
	s_waitcnt lgkmcnt(0)
	s_barrier
	s_waitcnt lgkmcnt(0)
	v_mfma_f32_16x16x32_bf16 v[124:127], v[154:157], v[194:197], v[124:127]
	v_mfma_f32_16x16x32_bf16 v[120:123], v[168:171], v[194:197], v[120:123]
	v_mfma_f32_16x16x32_bf16 v[108:111], v[154:157], v[202:205], v[108:111]
	v_mfma_f32_16x16x32_bf16 v[104:107], v[168:171], v[202:205], v[104:107]
	v_mfma_f32_16x16x32_bf16 v[92:95], v[154:157], v[210:213], v[92:95]
	v_mfma_f32_16x16x32_bf16 v[88:91], v[168:171], v[210:213], v[88:91]
	v_mfma_f32_16x16x32_bf16 v[76:79], v[154:157], v[218:221], v[76:79]
	v_mfma_f32_16x16x32_bf16 v[72:75], v[168:171], v[218:221], v[72:75]
	v_mfma_f32_16x16x32_bf16 v[124:127], v[164:167], v[198:201], v[124:127]
	v_mfma_f32_16x16x32_bf16 v[120:123], v[172:175], v[198:201], v[120:123]
	v_mfma_f32_16x16x32_bf16 v[108:111], v[164:167], v[206:209], v[108:111]
	v_mfma_f32_16x16x32_bf16 v[104:107], v[172:175], v[206:209], v[104:107]
	v_mfma_f32_16x16x32_bf16 v[92:95], v[164:167], v[214:217], v[92:95]
	v_mfma_f32_16x16x32_bf16 v[88:91], v[172:175], v[214:217], v[88:91]
	v_mfma_f32_16x16x32_bf16 v[76:79], v[164:167], v[222:225], v[76:79]
	v_mfma_f32_16x16x32_bf16 v[72:75], v[172:175], v[222:225], v[72:75]
	v_mfma_f32_16x16x32_bf16 v[116:119], v[176:179], v[194:197], v[116:119]
	v_mfma_f32_16x16x32_bf16 v[112:115], v[184:187], v[194:197], v[112:115]
	v_mfma_f32_16x16x32_bf16 v[100:103], v[176:179], v[202:205], v[100:103]
	v_mfma_f32_16x16x32_bf16 v[96:99], v[184:187], v[202:205], v[96:99]
	v_mfma_f32_16x16x32_bf16 v[84:87], v[176:179], v[210:213], v[84:87]
	v_mfma_f32_16x16x32_bf16 v[80:83], v[184:187], v[210:213], v[80:83]
	v_mfma_f32_16x16x32_bf16 v[68:71], v[176:179], v[218:221], v[68:71]
	v_mfma_f32_16x16x32_bf16 v[64:67], v[184:187], v[218:221], v[64:67]
	v_mfma_f32_16x16x32_bf16 v[116:119], v[180:183], v[198:201], v[116:119]
	v_mfma_f32_16x16x32_bf16 v[112:115], v[190:193], v[198:201], v[112:115]
	v_mfma_f32_16x16x32_bf16 v[100:103], v[180:183], v[206:209], v[100:103]
	v_mfma_f32_16x16x32_bf16 v[96:99], v[190:193], v[206:209], v[96:99]
	v_mfma_f32_16x16x32_bf16 v[84:87], v[180:183], v[214:217], v[84:87]
	v_mfma_f32_16x16x32_bf16 v[80:83], v[190:193], v[214:217], v[80:83]
	v_mfma_f32_16x16x32_bf16 v[68:71], v[180:183], v[222:225], v[68:71]
	v_mfma_f32_16x16x32_bf16 v[64:67], v[190:193], v[222:225], v[64:67]
	s_barrier
	s_add_i32 s63, s54, s26
	v_lshl_add_u64 v[226:227], s[44:45], 0, v[130:131]
	s_mov_b32 m0, s63
	s_setprio 2
	ds_read_b128 v[194:197], v161 offset:16384
	ds_read_b128 v[198:201], v161 offset:17408
	ds_read_b128 v[202:205], v161 offset:18432
	ds_read_b128 v[206:209], v161 offset:19456
	ds_read_b128 v[210:213], v161 offset:20480
	ds_read_b128 v[214:217], v161 offset:21504
	ds_read_b128 v[218:221], v161 offset:22528
	ds_read_b128 v[222:225], v161 offset:23552
	s_setprio 0
	global_load_lds_dwordx4 v[226:227], off
	s_add_i32 m0, s63, 0x2000
	s_add_u32 s64, s44, 0x80000
	v_lshl_add_u64 v[228:229], s[44:45], 0, v[134:135]
	s_addc_u32 s65, s45, 0
	s_add_i32 s63, s55, s26
	global_load_lds_dwordx4 v[228:229], off
	v_lshl_add_u64 v[230:231], s[64:65], 0, v[130:131]
	s_mov_b32 m0, s63
	v_lshl_add_u64 v[232:233], s[46:47], 0, v[132:133]
	global_load_lds_dwordx4 v[230:231], off
	v_lshl_add_u64 v[230:231], s[64:65], 0, v[134:135]
	s_add_i32 m0, s63, 0x2000
	s_nop 0
	global_load_lds_dwordx4 v[230:231], off
	v_lshl_add_u64 v[230:231], s[46:47], 0, v[128:129]
	s_mov_b32 m0, s27
	s_nop 0
	global_load_lds_dwordx4 v[230:231], off
	s_mov_b32 m0, s28
	s_nop 0
	global_load_lds_dwordx4 v[232:233], off
	s_waitcnt vmcnt(8)
	s_waitcnt lgkmcnt(0)
	s_barrier
	s_waitcnt lgkmcnt(0)
	v_mfma_f32_16x16x32_bf16 v[60:63], v[154:157], v[194:197], v[60:63]
	v_mfma_f32_16x16x32_bf16 v[56:59], v[168:171], v[194:197], v[56:59]
	v_mfma_f32_16x16x32_bf16 v[44:47], v[154:157], v[202:205], v[44:47]
	v_mfma_f32_16x16x32_bf16 v[40:43], v[168:171], v[202:205], v[40:43]
	v_mfma_f32_16x16x32_bf16 v[28:31], v[154:157], v[210:213], v[28:31]
	v_mfma_f32_16x16x32_bf16 v[24:27], v[168:171], v[210:213], v[24:27]
	v_mfma_f32_16x16x32_bf16 v[12:15], v[154:157], v[218:221], v[12:15]
	v_mfma_f32_16x16x32_bf16 v[8:11], v[168:171], v[218:221], v[8:11]
	v_mfma_f32_16x16x32_bf16 v[60:63], v[164:167], v[198:201], v[60:63]
	v_mfma_f32_16x16x32_bf16 v[56:59], v[172:175], v[198:201], v[56:59]
	v_mfma_f32_16x16x32_bf16 v[44:47], v[164:167], v[206:209], v[44:47]
	v_mfma_f32_16x16x32_bf16 v[40:43], v[172:175], v[206:209], v[40:43]
	v_mfma_f32_16x16x32_bf16 v[28:31], v[164:167], v[214:217], v[28:31]
	v_mfma_f32_16x16x32_bf16 v[24:27], v[172:175], v[214:217], v[24:27]
	v_mfma_f32_16x16x32_bf16 v[12:15], v[164:167], v[222:225], v[12:15]
	v_mfma_f32_16x16x32_bf16 v[8:11], v[172:175], v[222:225], v[8:11]
	v_mfma_f32_16x16x32_bf16 v[52:55], v[176:179], v[194:197], v[52:55]
	v_mfma_f32_16x16x32_bf16 v[48:51], v[184:187], v[194:197], v[48:51]
	v_mfma_f32_16x16x32_bf16 v[36:39], v[176:179], v[202:205], v[36:39]
	v_mfma_f32_16x16x32_bf16 v[32:35], v[184:187], v[202:205], v[32:35]
	v_mfma_f32_16x16x32_bf16 v[20:23], v[176:179], v[210:213], v[20:23]
	v_mfma_f32_16x16x32_bf16 v[16:19], v[184:187], v[210:213], v[16:19]
	v_mfma_f32_16x16x32_bf16 v[4:7], v[176:179], v[218:221], v[4:7]
	v_mfma_f32_16x16x32_bf16 v[0:3], v[184:187], v[218:221], v[0:3]
	v_mfma_f32_16x16x32_bf16 v[52:55], v[180:183], v[198:201], v[52:55]
	v_mfma_f32_16x16x32_bf16 v[48:51], v[190:193], v[198:201], v[48:51]
	v_mfma_f32_16x16x32_bf16 v[36:39], v[180:183], v[206:209], v[36:39]
	v_mfma_f32_16x16x32_bf16 v[32:35], v[190:193], v[206:209], v[32:35]
	v_mfma_f32_16x16x32_bf16 v[20:23], v[180:183], v[214:217], v[20:23]
	v_mfma_f32_16x16x32_bf16 v[16:19], v[190:193], v[214:217], v[16:19]
	v_mfma_f32_16x16x32_bf16 v[4:7], v[180:183], v[222:225], v[4:7]
	v_mfma_f32_16x16x32_bf16 v[0:3], v[190:193], v[222:225], v[0:3]
	s_barrier
	s_add_i32 s63, 0, 0x18000
	v_add_u32_e32 v136, s63, v159
	s_add_i32 s64, 0, 0x1c000
	s_setprio 2
	ds_read_b128 v[154:157], v136
	ds_read_b128 v[164:167], v136 offset:1024
	ds_read_b128 v[168:171], v136 offset:2048
	ds_read_b128 v[172:175], v136 offset:3072
	v_add_u32_e32 v136, s64, v159
	ds_read_b128 v[176:179], v136
	ds_read_b128 v[180:183], v136 offset:1024
	ds_read_b128 v[184:187], v136 offset:2048
	ds_read_b128 v[190:193], v136 offset:3072
	s_add_u32 s46, s46, 0x80000
	s_addc_u32 s47, s47, 0
	s_mov_b32 m0, s29
	v_lshl_add_u64 v[234:235], s[46:47], 0, v[128:129]
	ds_read_b128 v[194:197], v161 offset:32768
	ds_read_b128 v[198:201], v161 offset:33792
	ds_read_b128 v[202:205], v161 offset:34816
	ds_read_b128 v[206:209], v161 offset:35840
	ds_read_b128 v[210:213], v161 offset:36864
	ds_read_b128 v[214:217], v161 offset:37888
	ds_read_b128 v[218:221], v161 offset:38912
	ds_read_b128 v[222:225], v161 offset:39936
	s_setprio 0
	global_load_lds_dwordx4 v[234:235], off
	v_lshl_add_u64 v[234:235], s[46:47], 0, v[132:133]
	s_mov_b32 m0, s33
	s_nop 0
	global_load_lds_dwordx4 v[234:235], off
	s_waitcnt vmcnt(8)
	s_waitcnt lgkmcnt(0)
	s_barrier
	s_waitcnt lgkmcnt(0)
	v_mfma_f32_16x16x32_bf16 v[124:127], v[154:157], v[194:197], v[124:127]
	v_mfma_f32_16x16x32_bf16 v[120:123], v[168:171], v[194:197], v[120:123]
	v_mfma_f32_16x16x32_bf16 v[108:111], v[154:157], v[202:205], v[108:111]
	v_mfma_f32_16x16x32_bf16 v[104:107], v[168:171], v[202:205], v[104:107]
	v_mfma_f32_16x16x32_bf16 v[92:95], v[154:157], v[210:213], v[92:95]
	v_mfma_f32_16x16x32_bf16 v[88:91], v[168:171], v[210:213], v[88:91]
	v_mfma_f32_16x16x32_bf16 v[76:79], v[154:157], v[218:221], v[76:79]
	v_mfma_f32_16x16x32_bf16 v[72:75], v[168:171], v[218:221], v[72:75]
	v_mfma_f32_16x16x32_bf16 v[124:127], v[164:167], v[198:201], v[124:127]
	v_mfma_f32_16x16x32_bf16 v[120:123], v[172:175], v[198:201], v[120:123]
	v_mfma_f32_16x16x32_bf16 v[108:111], v[164:167], v[206:209], v[108:111]
	v_mfma_f32_16x16x32_bf16 v[104:107], v[172:175], v[206:209], v[104:107]
	v_mfma_f32_16x16x32_bf16 v[92:95], v[164:167], v[214:217], v[92:95]
	v_mfma_f32_16x16x32_bf16 v[88:91], v[172:175], v[214:217], v[88:91]
	v_mfma_f32_16x16x32_bf16 v[76:79], v[164:167], v[222:225], v[76:79]
	v_mfma_f32_16x16x32_bf16 v[72:75], v[172:175], v[222:225], v[72:75]
	v_mfma_f32_16x16x32_bf16 v[116:119], v[176:179], v[194:197], v[116:119]
	v_mfma_f32_16x16x32_bf16 v[112:115], v[184:187], v[194:197], v[112:115]
	v_mfma_f32_16x16x32_bf16 v[100:103], v[176:179], v[202:205], v[100:103]
	v_mfma_f32_16x16x32_bf16 v[96:99], v[184:187], v[202:205], v[96:99]
	v_mfma_f32_16x16x32_bf16 v[84:87], v[176:179], v[210:213], v[84:87]
	v_mfma_f32_16x16x32_bf16 v[80:83], v[184:187], v[210:213], v[80:83]
	v_mfma_f32_16x16x32_bf16 v[68:71], v[176:179], v[218:221], v[68:71]
	v_mfma_f32_16x16x32_bf16 v[64:67], v[184:187], v[218:221], v[64:67]
	v_mfma_f32_16x16x32_bf16 v[116:119], v[180:183], v[198:201], v[116:119]
	v_mfma_f32_16x16x32_bf16 v[112:115], v[190:193], v[198:201], v[112:115]
	v_mfma_f32_16x16x32_bf16 v[100:103], v[180:183], v[206:209], v[100:103]
	v_mfma_f32_16x16x32_bf16 v[96:99], v[190:193], v[206:209], v[96:99]
	v_mfma_f32_16x16x32_bf16 v[84:87], v[180:183], v[214:217], v[84:87]
	v_mfma_f32_16x16x32_bf16 v[80:83], v[190:193], v[214:217], v[80:83]
	v_mfma_f32_16x16x32_bf16 v[68:71], v[180:183], v[222:225], v[68:71]
	v_mfma_f32_16x16x32_bf16 v[64:67], v[190:193], v[222:225], v[64:67]
	s_barrier
	s_add_i32 s46, s63, s26
	v_lshl_add_u64 v[226:227], v[226:227], 0, s[18:19]
	s_mov_b32 m0, s46
	s_setprio 2
	ds_read_b128 v[194:197], v161 offset:49152
	ds_read_b128 v[198:201], v161 offset:50176
	ds_read_b128 v[202:205], v161 offset:51200
	ds_read_b128 v[206:209], v161 offset:52224
	ds_read_b128 v[210:213], v161 offset:53248
	ds_read_b128 v[214:217], v161 offset:54272
	ds_read_b128 v[218:221], v161 offset:55296
	ds_read_b128 v[222:225], v161 offset:56320
	s_setprio 0
	global_load_lds_dwordx4 v[226:227], off
	s_add_i32 m0, s46, 0x2000
	s_add_u32 s44, s44, 0x80080
	v_lshl_add_u64 v[226:227], v[228:229], 0, s[18:19]
	s_addc_u32 s45, s45, 0
	s_add_i32 s46, s64, s26
	global_load_lds_dwordx4 v[226:227], off
	v_lshl_add_u64 v[226:227], s[44:45], 0, v[130:131]
	s_mov_b32 m0, s46
	s_nop 0
	global_load_lds_dwordx4 v[226:227], off
	v_lshl_add_u64 v[226:227], s[44:45], 0, v[134:135]
	s_add_i32 m0, s46, 0x2000
	s_nop 0
	global_load_lds_dwordx4 v[226:227], off
	v_lshl_add_u64 v[226:227], v[230:231], 0, s[18:19]
	s_mov_b32 m0, s50
	s_nop 0
	global_load_lds_dwordx4 v[226:227], off
	v_lshl_add_u64 v[226:227], v[232:233], 0, s[18:19]
	s_mov_b32 m0, s51
	s_nop 0
	global_load_lds_dwordx4 v[226:227], off
	s_waitcnt vmcnt(8)
	s_waitcnt lgkmcnt(0)
	s_barrier
	s_waitcnt lgkmcnt(0)
	v_mfma_f32_16x16x32_bf16 v[60:63], v[154:157], v[194:197], v[60:63]
	v_mfma_f32_16x16x32_bf16 v[56:59], v[168:171], v[194:197], v[56:59]
	v_mfma_f32_16x16x32_bf16 v[44:47], v[154:157], v[202:205], v[44:47]
	v_mfma_f32_16x16x32_bf16 v[40:43], v[168:171], v[202:205], v[40:43]
	v_mfma_f32_16x16x32_bf16 v[28:31], v[154:157], v[210:213], v[28:31]
	v_mfma_f32_16x16x32_bf16 v[24:27], v[168:171], v[210:213], v[24:27]
	v_mfma_f32_16x16x32_bf16 v[12:15], v[154:157], v[218:221], v[12:15]
	v_mfma_f32_16x16x32_bf16 v[8:11], v[168:171], v[218:221], v[8:11]
	v_mfma_f32_16x16x32_bf16 v[60:63], v[164:167], v[198:201], v[60:63]
	v_mfma_f32_16x16x32_bf16 v[56:59], v[172:175], v[198:201], v[56:59]
	v_mfma_f32_16x16x32_bf16 v[44:47], v[164:167], v[206:209], v[44:47]
	v_mfma_f32_16x16x32_bf16 v[40:43], v[172:175], v[206:209], v[40:43]
	v_mfma_f32_16x16x32_bf16 v[28:31], v[164:167], v[214:217], v[28:31]
	v_mfma_f32_16x16x32_bf16 v[24:27], v[172:175], v[214:217], v[24:27]
	v_mfma_f32_16x16x32_bf16 v[12:15], v[164:167], v[222:225], v[12:15]
	v_mfma_f32_16x16x32_bf16 v[8:11], v[172:175], v[222:225], v[8:11]
	v_mfma_f32_16x16x32_bf16 v[52:55], v[176:179], v[194:197], v[52:55]
	v_mfma_f32_16x16x32_bf16 v[48:51], v[184:187], v[194:197], v[48:51]
	v_mfma_f32_16x16x32_bf16 v[36:39], v[176:179], v[202:205], v[36:39]
	v_mfma_f32_16x16x32_bf16 v[32:35], v[184:187], v[202:205], v[32:35]
	v_mfma_f32_16x16x32_bf16 v[20:23], v[176:179], v[210:213], v[20:23]
	v_mfma_f32_16x16x32_bf16 v[16:19], v[184:187], v[210:213], v[16:19]
	v_mfma_f32_16x16x32_bf16 v[4:7], v[176:179], v[218:221], v[4:7]
	v_mfma_f32_16x16x32_bf16 v[0:3], v[184:187], v[218:221], v[0:3]
	v_mfma_f32_16x16x32_bf16 v[52:55], v[180:183], v[198:201], v[52:55]
	v_mfma_f32_16x16x32_bf16 v[48:51], v[190:193], v[198:201], v[48:51]
	v_mfma_f32_16x16x32_bf16 v[36:39], v[180:183], v[206:209], v[36:39]
	v_mfma_f32_16x16x32_bf16 v[32:35], v[190:193], v[206:209], v[32:35]
	v_mfma_f32_16x16x32_bf16 v[20:23], v[180:183], v[214:217], v[20:23]
	v_mfma_f32_16x16x32_bf16 v[16:19], v[190:193], v[214:217], v[16:19]
	v_mfma_f32_16x16x32_bf16 v[4:7], v[180:183], v[222:225], v[4:7]
	v_mfma_f32_16x16x32_bf16 v[0:3], v[190:193], v[222:225], v[0:3]
	s_barrier
	s_add_i32 s62, s62, 2
	s_add_u32 s10, s10, 0x100
	s_addc_u32 s11, s11, 0
	s_add_u32 s60, s60, 0x100
	s_addc_u32 s61, s61, 0
	s_cmp_gt_u32 s62, 29
	s_cbranch_scc0 .LBB0_838
	s_and_b64 vcc, exec, s[20:21]
	s_cbranch_vccnz .LBB0_843
	v_lshl_add_u32 v154, s6, 8, v158
	s_cmp_gt_i32 s42, 3
	s_mov_b64 s[6:7], -1
	s_cbranch_scc1 .LBB0_844

.LBB0_947:
	s_setprio 2
	ds_read_b128 v[154:157], v137
	ds_read_b128 v[158:161], v137 offset:1024
	ds_read_b128 v[174:177], v137 offset:2048
	ds_read_b128 v[178:181], v137 offset:3072
	ds_read_b128 v[182:185], v170
	ds_read_b128 v[190:193], v170 offset:1024
	ds_read_b128 v[194:197], v170 offset:2048
	ds_read_b128 v[198:201], v170 offset:3072
	s_add_u32 s34, s10, 0xfffe0080
	s_addc_u32 s35, s11, -1
	s_cmp_eq_u32 s53, 4
	s_cselect_b32 s37, s5, s35
	s_cselect_b32 s36, s9, s34
	s_cselect_b32 s35, s13, s52
	s_cselect_b32 s34, s16, s51
	v_lshl_add_u64 v[186:187], s[10:11], 0, v[146:147]
	s_add_i32 m0, s15, 0xc000
	ds_read_b128 v[202:205], v171
	ds_read_b128 v[206:209], v171 offset:1024
	ds_read_b128 v[210:213], v171 offset:2048
	ds_read_b128 v[214:217], v171 offset:3072
	ds_read_b128 v[218:221], v171 offset:4096
	ds_read_b128 v[222:225], v171 offset:5120
	ds_read_b128 v[226:229], v171 offset:6144
	ds_read_b128 v[230:233], v171 offset:7168
	s_setprio 0
	global_load_lds_dwordx4 v[186:187], off
	v_lshl_add_u64 v[186:187], s[10:11], 0, v[148:149]
	s_add_i32 m0, s15, 0xe000
	s_nop 0
	global_load_lds_dwordx4 v[186:187], off
	s_waitcnt vmcnt(8)
	s_waitcnt lgkmcnt(0)
	s_barrier
	s_waitcnt lgkmcnt(0)
	v_mfma_f32_16x16x32_bf16 v[124:127], v[154:157], v[202:205], v[124:127]
	v_mfma_f32_16x16x32_bf16 v[120:123], v[174:177], v[202:205], v[120:123]
	v_mfma_f32_16x16x32_bf16 v[108:111], v[154:157], v[210:213], v[108:111]
	v_mfma_f32_16x16x32_bf16 v[104:107], v[174:177], v[210:213], v[104:107]
	v_mfma_f32_16x16x32_bf16 v[92:95], v[154:157], v[218:221], v[92:95]
	v_mfma_f32_16x16x32_bf16 v[88:91], v[174:177], v[218:221], v[88:91]
	v_mfma_f32_16x16x32_bf16 v[76:79], v[154:157], v[226:229], v[76:79]
	v_mfma_f32_16x16x32_bf16 v[72:75], v[174:177], v[226:229], v[72:75]
	v_mfma_f32_16x16x32_bf16 v[124:127], v[158:161], v[206:209], v[124:127]
	v_mfma_f32_16x16x32_bf16 v[120:123], v[178:181], v[206:209], v[120:123]
	v_mfma_f32_16x16x32_bf16 v[108:111], v[158:161], v[214:217], v[108:111]
	v_mfma_f32_16x16x32_bf16 v[104:107], v[178:181], v[214:217], v[104:107]
	v_mfma_f32_16x16x32_bf16 v[92:95], v[158:161], v[222:225], v[92:95]
	v_mfma_f32_16x16x32_bf16 v[88:91], v[178:181], v[222:225], v[88:91]
	v_mfma_f32_16x16x32_bf16 v[76:79], v[158:161], v[230:233], v[76:79]
	v_mfma_f32_16x16x32_bf16 v[72:75], v[178:181], v[230:233], v[72:75]
	v_mfma_f32_16x16x32_bf16 v[116:119], v[182:185], v[202:205], v[116:119]
	v_mfma_f32_16x16x32_bf16 v[112:115], v[194:197], v[202:205], v[112:115]
	v_mfma_f32_16x16x32_bf16 v[100:103], v[182:185], v[210:213], v[100:103]
	v_mfma_f32_16x16x32_bf16 v[96:99], v[194:197], v[210:213], v[96:99]
	v_mfma_f32_16x16x32_bf16 v[84:87], v[182:185], v[218:221], v[84:87]
	v_mfma_f32_16x16x32_bf16 v[80:83], v[194:197], v[218:221], v[80:83]
	v_mfma_f32_16x16x32_bf16 v[68:71], v[182:185], v[226:229], v[68:71]
	v_mfma_f32_16x16x32_bf16 v[64:67], v[194:197], v[226:229], v[64:67]
	v_mfma_f32_16x16x32_bf16 v[116:119], v[190:193], v[206:209], v[116:119]
	v_mfma_f32_16x16x32_bf16 v[112:115], v[198:201], v[206:209], v[112:115]
	v_mfma_f32_16x16x32_bf16 v[100:103], v[190:193], v[214:217], v[100:103]
	v_mfma_f32_16x16x32_bf16 v[96:99], v[198:201], v[214:217], v[96:99]
	v_mfma_f32_16x16x32_bf16 v[84:87], v[190:193], v[222:225], v[84:87]
	v_mfma_f32_16x16x32_bf16 v[80:83], v[198:201], v[222:225], v[80:83]
	v_mfma_f32_16x16x32_bf16 v[68:71], v[190:193], v[230:233], v[68:71]
	v_mfma_f32_16x16x32_bf16 v[64:67], v[198:201], v[230:233], v[64:67]
	s_barrier
	s_add_i32 s54, s47, s26
	v_lshl_add_u64 v[186:187], s[34:35], 0, v[130:131]
	s_mov_b32 m0, s54
	s_setprio 2
	ds_read_b128 v[202:205], v171 offset:16384
	ds_read_b128 v[206:209], v171 offset:17408
	ds_read_b128 v[210:213], v171 offset:18432
	ds_read_b128 v[214:217], v171 offset:19456
	ds_read_b128 v[218:221], v171 offset:20480
	ds_read_b128 v[222:225], v171 offset:21504
	ds_read_b128 v[226:229], v171 offset:22528
	ds_read_b128 v[230:233], v171 offset:23552
	s_setprio 0
	global_load_lds_dwordx4 v[186:187], off
	s_add_i32 m0, s54, 0x2000
	s_add_u32 s54, s34, 0x20000
	v_lshl_add_u64 v[234:235], s[34:35], 0, v[134:135]
	s_addc_u32 s55, s35, 0
	s_add_i32 s58, s48, s26
	global_load_lds_dwordx4 v[234:235], off
	v_lshl_add_u64 v[236:237], s[54:55], 0, v[130:131]
	s_mov_b32 m0, s58
	v_lshl_add_u64 v[238:239], s[36:37], 0, v[132:133]
	global_load_lds_dwordx4 v[236:237], off
	v_lshl_add_u64 v[236:237], s[54:55], 0, v[134:135]
	s_add_i32 m0, s58, 0x2000
	s_nop 0
	global_load_lds_dwordx4 v[236:237], off
	v_lshl_add_u64 v[236:237], s[36:37], 0, v[128:129]
	s_mov_b32 m0, s15
	s_nop 0
	global_load_lds_dwordx4 v[236:237], off
	s_mov_b32 m0, s27
	s_nop 0
	global_load_lds_dwordx4 v[238:239], off
	s_waitcnt vmcnt(8)
	s_waitcnt lgkmcnt(0)
	s_barrier
	s_waitcnt lgkmcnt(0)
	v_mfma_f32_16x16x32_bf16 v[60:63], v[154:157], v[202:205], v[60:63]
	v_mfma_f32_16x16x32_bf16 v[56:59], v[174:177], v[202:205], v[56:59]
	v_mfma_f32_16x16x32_bf16 v[44:47], v[154:157], v[210:213], v[44:47]
	v_mfma_f32_16x16x32_bf16 v[40:43], v[174:177], v[210:213], v[40:43]
	v_mfma_f32_16x16x32_bf16 v[28:31], v[154:157], v[218:221], v[28:31]
	v_mfma_f32_16x16x32_bf16 v[24:27], v[174:177], v[218:221], v[24:27]
	v_mfma_f32_16x16x32_bf16 v[12:15], v[154:157], v[226:229], v[12:15]
	v_mfma_f32_16x16x32_bf16 v[8:11], v[174:177], v[226:229], v[8:11]
	v_mfma_f32_16x16x32_bf16 v[60:63], v[158:161], v[206:209], v[60:63]
	v_mfma_f32_16x16x32_bf16 v[56:59], v[178:181], v[206:209], v[56:59]
	v_mfma_f32_16x16x32_bf16 v[44:47], v[158:161], v[214:217], v[44:47]
	v_mfma_f32_16x16x32_bf16 v[40:43], v[178:181], v[214:217], v[40:43]
	v_mfma_f32_16x16x32_bf16 v[28:31], v[158:161], v[222:225], v[28:31]
	v_mfma_f32_16x16x32_bf16 v[24:27], v[178:181], v[222:225], v[24:27]
	v_mfma_f32_16x16x32_bf16 v[12:15], v[158:161], v[230:233], v[12:15]
	v_mfma_f32_16x16x32_bf16 v[8:11], v[178:181], v[230:233], v[8:11]
	v_mfma_f32_16x16x32_bf16 v[52:55], v[182:185], v[202:205], v[52:55]
	v_mfma_f32_16x16x32_bf16 v[48:51], v[194:197], v[202:205], v[48:51]
	v_mfma_f32_16x16x32_bf16 v[36:39], v[182:185], v[210:213], v[36:39]
	v_mfma_f32_16x16x32_bf16 v[32:35], v[194:197], v[210:213], v[32:35]
	v_mfma_f32_16x16x32_bf16 v[20:23], v[182:185], v[218:221], v[20:23]
	v_mfma_f32_16x16x32_bf16 v[16:19], v[194:197], v[218:221], v[16:19]
	v_mfma_f32_16x16x32_bf16 v[4:7], v[182:185], v[226:229], v[4:7]
	v_mfma_f32_16x16x32_bf16 v[0:3], v[194:197], v[226:229], v[0:3]
	v_mfma_f32_16x16x32_bf16 v[52:55], v[190:193], v[206:209], v[52:55]
	v_mfma_f32_16x16x32_bf16 v[48:51], v[198:201], v[206:209], v[48:51]
	v_mfma_f32_16x16x32_bf16 v[36:39], v[190:193], v[214:217], v[36:39]
	v_mfma_f32_16x16x32_bf16 v[32:35], v[198:201], v[214:217], v[32:35]
	v_mfma_f32_16x16x32_bf16 v[20:23], v[190:193], v[222:225], v[20:23]
	v_mfma_f32_16x16x32_bf16 v[16:19], v[198:201], v[222:225], v[16:19]
	v_mfma_f32_16x16x32_bf16 v[4:7], v[190:193], v[230:233], v[4:7]
	v_mfma_f32_16x16x32_bf16 v[0:3], v[198:201], v[230:233], v[0:3]
	s_barrier
	s_add_i32 s54, 0, 0x18000
	v_add_u32_e32 v138, s54, v169
	s_add_i32 s55, 0, 0x1c000
	s_setprio 2
	ds_read_b128 v[154:157], v138
	ds_read_b128 v[158:161], v138 offset:1024
	ds_read_b128 v[174:177], v138 offset:2048
	ds_read_b128 v[178:181], v138 offset:3072
	v_add_u32_e32 v138, s55, v169
	ds_read_b128 v[182:185], v138
	ds_read_b128 v[190:193], v138 offset:1024
	ds_read_b128 v[194:197], v138 offset:2048
	ds_read_b128 v[198:201], v138 offset:3072
	s_add_u32 s36, s36, 0x20000
	s_addc_u32 s37, s37, 0
	s_mov_b32 m0, s38
	v_lshl_add_u64 v[240:241], s[36:37], 0, v[128:129]
	ds_read_b128 v[202:205], v171 offset:32768
	ds_read_b128 v[206:209], v171 offset:33792
	ds_read_b128 v[210:213], v171 offset:34816
	ds_read_b128 v[214:217], v171 offset:35840
	ds_read_b128 v[218:221], v171 offset:36864
	ds_read_b128 v[222:225], v171 offset:37888
	ds_read_b128 v[226:229], v171 offset:38912
	ds_read_b128 v[230:233], v171 offset:39936
	s_setprio 0
	global_load_lds_dwordx4 v[240:241], off
	v_lshl_add_u64 v[240:241], s[36:37], 0, v[132:133]
	s_mov_b32 m0, s39
	s_nop 0
	global_load_lds_dwordx4 v[240:241], off
	s_waitcnt vmcnt(8)
	s_waitcnt lgkmcnt(0)
	s_barrier
	s_waitcnt lgkmcnt(0)
	v_mfma_f32_16x16x32_bf16 v[124:127], v[154:157], v[202:205], v[124:127]
	v_mfma_f32_16x16x32_bf16 v[120:123], v[174:177], v[202:205], v[120:123]
	v_mfma_f32_16x16x32_bf16 v[108:111], v[154:157], v[210:213], v[108:111]
	v_mfma_f32_16x16x32_bf16 v[104:107], v[174:177], v[210:213], v[104:107]
	v_mfma_f32_16x16x32_bf16 v[92:95], v[154:157], v[218:221], v[92:95]
	v_mfma_f32_16x16x32_bf16 v[88:91], v[174:177], v[218:221], v[88:91]
	v_mfma_f32_16x16x32_bf16 v[76:79], v[154:157], v[226:229], v[76:79]
	v_mfma_f32_16x16x32_bf16 v[72:75], v[174:177], v[226:229], v[72:75]
	v_mfma_f32_16x16x32_bf16 v[124:127], v[158:161], v[206:209], v[124:127]
	v_mfma_f32_16x16x32_bf16 v[120:123], v[178:181], v[206:209], v[120:123]
	v_mfma_f32_16x16x32_bf16 v[108:111], v[158:161], v[214:217], v[108:111]
	v_mfma_f32_16x16x32_bf16 v[104:107], v[178:181], v[214:217], v[104:107]
	v_mfma_f32_16x16x32_bf16 v[92:95], v[158:161], v[222:225], v[92:95]
	v_mfma_f32_16x16x32_bf16 v[88:91], v[178:181], v[222:225], v[88:91]
	v_mfma_f32_16x16x32_bf16 v[76:79], v[158:161], v[230:233], v[76:79]
	v_mfma_f32_16x16x32_bf16 v[72:75], v[178:181], v[230:233], v[72:75]
	v_mfma_f32_16x16x32_bf16 v[116:119], v[182:185], v[202:205], v[116:119]
	v_mfma_f32_16x16x32_bf16 v[112:115], v[194:197], v[202:205], v[112:115]
	v_mfma_f32_16x16x32_bf16 v[100:103], v[182:185], v[210:213], v[100:103]
	v_mfma_f32_16x16x32_bf16 v[96:99], v[194:197], v[210:213], v[96:99]
	v_mfma_f32_16x16x32_bf16 v[84:87], v[182:185], v[218:221], v[84:87]
	v_mfma_f32_16x16x32_bf16 v[80:83], v[194:197], v[218:221], v[80:83]
	v_mfma_f32_16x16x32_bf16 v[68:71], v[182:185], v[226:229], v[68:71]
	v_mfma_f32_16x16x32_bf16 v[64:67], v[194:197], v[226:229], v[64:67]
	v_mfma_f32_16x16x32_bf16 v[116:119], v[190:193], v[206:209], v[116:119]
	v_mfma_f32_16x16x32_bf16 v[112:115], v[198:201], v[206:209], v[112:115]
	v_mfma_f32_16x16x32_bf16 v[100:103], v[190:193], v[214:217], v[100:103]
	v_mfma_f32_16x16x32_bf16 v[96:99], v[198:201], v[214:217], v[96:99]
	v_mfma_f32_16x16x32_bf16 v[84:87], v[190:193], v[222:225], v[84:87]
	v_mfma_f32_16x16x32_bf16 v[80:83], v[198:201], v[222:225], v[80:83]
	v_mfma_f32_16x16x32_bf16 v[68:71], v[190:193], v[230:233], v[68:71]
	v_mfma_f32_16x16x32_bf16 v[64:67], v[198:201], v[230:233], v[64:67]
	s_barrier
	s_add_i32 s36, s54, s26
	v_lshl_add_u64 v[186:187], v[186:187], 0, s[20:21]
	s_mov_b32 m0, s36
	s_setprio 2
	ds_read_b128 v[202:205], v171 offset:49152
	ds_read_b128 v[206:209], v171 offset:50176
	ds_read_b128 v[210:213], v171 offset:51200
	ds_read_b128 v[214:217], v171 offset:52224
	ds_read_b128 v[218:221], v171 offset:53248
	ds_read_b128 v[222:225], v171 offset:54272
	ds_read_b128 v[226:229], v171 offset:55296
	ds_read_b128 v[230:233], v171 offset:56320
	s_setprio 0
	global_load_lds_dwordx4 v[186:187], off
	s_add_i32 m0, s36, 0x2000
	s_add_u32 s34, s34, 0x20080
	v_lshl_add_u64 v[186:187], v[234:235], 0, s[20:21]
	s_addc_u32 s35, s35, 0
	s_add_i32 s36, s55, s26
	global_load_lds_dwordx4 v[186:187], off
	v_lshl_add_u64 v[186:187], s[34:35], 0, v[130:131]
	s_mov_b32 m0, s36
	s_nop 0
	global_load_lds_dwordx4 v[186:187], off
	v_lshl_add_u64 v[186:187], s[34:35], 0, v[134:135]
	s_add_i32 m0, s36, 0x2000
	s_nop 0
	global_load_lds_dwordx4 v[186:187], off
	v_lshl_add_u64 v[186:187], v[236:237], 0, s[20:21]
	s_mov_b32 m0, s41
	s_nop 0
	global_load_lds_dwordx4 v[186:187], off
	v_lshl_add_u64 v[186:187], v[238:239], 0, s[20:21]
	s_mov_b32 m0, s42
	s_nop 0
	global_load_lds_dwordx4 v[186:187], off
	s_waitcnt vmcnt(8)
	s_waitcnt lgkmcnt(0)
	s_barrier
	s_waitcnt lgkmcnt(0)
	v_mfma_f32_16x16x32_bf16 v[60:63], v[154:157], v[202:205], v[60:63]
	v_mfma_f32_16x16x32_bf16 v[56:59], v[174:177], v[202:205], v[56:59]
	v_mfma_f32_16x16x32_bf16 v[44:47], v[154:157], v[210:213], v[44:47]
	v_mfma_f32_16x16x32_bf16 v[40:43], v[174:177], v[210:213], v[40:43]
	v_mfma_f32_16x16x32_bf16 v[28:31], v[154:157], v[218:221], v[28:31]
	v_mfma_f32_16x16x32_bf16 v[24:27], v[174:177], v[218:221], v[24:27]
	v_mfma_f32_16x16x32_bf16 v[12:15], v[154:157], v[226:229], v[12:15]
	v_mfma_f32_16x16x32_bf16 v[8:11], v[174:177], v[226:229], v[8:11]
	v_mfma_f32_16x16x32_bf16 v[60:63], v[158:161], v[206:209], v[60:63]
	v_mfma_f32_16x16x32_bf16 v[56:59], v[178:181], v[206:209], v[56:59]
	v_mfma_f32_16x16x32_bf16 v[44:47], v[158:161], v[214:217], v[44:47]
	v_mfma_f32_16x16x32_bf16 v[40:43], v[178:181], v[214:217], v[40:43]
	v_mfma_f32_16x16x32_bf16 v[28:31], v[158:161], v[222:225], v[28:31]
	v_mfma_f32_16x16x32_bf16 v[24:27], v[178:181], v[222:225], v[24:27]
	v_mfma_f32_16x16x32_bf16 v[12:15], v[158:161], v[230:233], v[12:15]
	v_mfma_f32_16x16x32_bf16 v[8:11], v[178:181], v[230:233], v[8:11]
	v_mfma_f32_16x16x32_bf16 v[52:55], v[182:185], v[202:205], v[52:55]
	v_mfma_f32_16x16x32_bf16 v[48:51], v[194:197], v[202:205], v[48:51]
	v_mfma_f32_16x16x32_bf16 v[36:39], v[182:185], v[210:213], v[36:39]
	v_mfma_f32_16x16x32_bf16 v[32:35], v[194:197], v[210:213], v[32:35]
	v_mfma_f32_16x16x32_bf16 v[20:23], v[182:185], v[218:221], v[20:23]
	v_mfma_f32_16x16x32_bf16 v[16:19], v[194:197], v[218:221], v[16:19]
	v_mfma_f32_16x16x32_bf16 v[4:7], v[182:185], v[226:229], v[4:7]
	v_mfma_f32_16x16x32_bf16 v[0:3], v[194:197], v[226:229], v[0:3]
	v_mfma_f32_16x16x32_bf16 v[52:55], v[190:193], v[206:209], v[52:55]
	v_mfma_f32_16x16x32_bf16 v[48:51], v[198:201], v[206:209], v[48:51]
	v_mfma_f32_16x16x32_bf16 v[36:39], v[190:193], v[214:217], v[36:39]
	v_mfma_f32_16x16x32_bf16 v[32:35], v[198:201], v[214:217], v[32:35]
	v_mfma_f32_16x16x32_bf16 v[20:23], v[190:193], v[222:225], v[20:23]
	v_mfma_f32_16x16x32_bf16 v[16:19], v[198:201], v[222:225], v[16:19]
	v_mfma_f32_16x16x32_bf16 v[4:7], v[190:193], v[230:233], v[4:7]
	v_mfma_f32_16x16x32_bf16 v[0:3], v[198:201], v[230:233], v[0:3]
	s_barrier
	s_add_i32 s53, s53, 2
	s_add_u32 s10, s10, 0x100
	s_addc_u32 s11, s11, 0
	s_add_u32 s51, s51, 0x100
	s_addc_u32 s52, s52, 0
	s_cmp_gt_u32 s53, 5
	s_cbranch_scc0 .LBB0_947
	s_and_b64 vcc, exec, s[22:23]
	s_cbranch_vccz .LBB0_950
	s_barrier

.LBB0_1037:
	s_setprio 2
	ds_read_b128 v[148:151], v160
	ds_read_b128 v[152:155], v160 offset:1024
	ds_read_b128 v[166:169], v160 offset:2048
	ds_read_b128 v[170:173], v160 offset:3072
	ds_read_b128 v[174:177], v161
	ds_read_b128 v[178:181], v161 offset:1024
	ds_read_b128 v[182:185], v161 offset:2048
	ds_read_b128 v[190:193], v161 offset:3072
	s_add_u32 s34, s10, 0xfffe0080
	s_addc_u32 s35, s11, -1
	s_cmp_eq_u32 s51, 4
	s_cselect_b32 s37, s5, s35
	s_cselect_b32 s36, s12, s34
	s_cselect_b32 s35, s23, s50
	s_cselect_b32 s34, s27, s49
	v_lshl_add_u64 v[156:157], s[10:11], 0, v[140:141]
	s_add_i32 m0, s9, 0xc000
	ds_read_b128 v[194:197], v162
	ds_read_b128 v[198:201], v162 offset:1024
	ds_read_b128 v[202:205], v162 offset:2048
	ds_read_b128 v[206:209], v162 offset:3072
	ds_read_b128 v[210:213], v162 offset:4096
	ds_read_b128 v[214:217], v162 offset:5120
	ds_read_b128 v[218:221], v162 offset:6144
	ds_read_b128 v[222:225], v162 offset:7168
	s_setprio 0
	global_load_lds_dwordx4 v[156:157], off
	v_lshl_add_u64 v[156:157], s[10:11], 0, v[142:143]
	s_add_i32 m0, s9, 0xe000
	s_nop 0
	global_load_lds_dwordx4 v[156:157], off
	s_waitcnt vmcnt(8)
	s_waitcnt lgkmcnt(0)
	s_barrier
	s_waitcnt lgkmcnt(0)
	v_mfma_f32_16x16x32_bf16 v[124:127], v[148:151], v[194:197], v[124:127]
	v_mfma_f32_16x16x32_bf16 v[120:123], v[166:169], v[194:197], v[120:123]
	v_mfma_f32_16x16x32_bf16 v[108:111], v[148:151], v[202:205], v[108:111]
	v_mfma_f32_16x16x32_bf16 v[104:107], v[166:169], v[202:205], v[104:107]
	v_mfma_f32_16x16x32_bf16 v[92:95], v[148:151], v[210:213], v[92:95]
	v_mfma_f32_16x16x32_bf16 v[88:91], v[166:169], v[210:213], v[88:91]
	v_mfma_f32_16x16x32_bf16 v[76:79], v[148:151], v[218:221], v[76:79]
	v_mfma_f32_16x16x32_bf16 v[72:75], v[166:169], v[218:221], v[72:75]
	v_mfma_f32_16x16x32_bf16 v[124:127], v[152:155], v[198:201], v[124:127]
	v_mfma_f32_16x16x32_bf16 v[120:123], v[170:173], v[198:201], v[120:123]
	v_mfma_f32_16x16x32_bf16 v[108:111], v[152:155], v[206:209], v[108:111]
	v_mfma_f32_16x16x32_bf16 v[104:107], v[170:173], v[206:209], v[104:107]
	v_mfma_f32_16x16x32_bf16 v[92:95], v[152:155], v[214:217], v[92:95]
	v_mfma_f32_16x16x32_bf16 v[88:91], v[170:173], v[214:217], v[88:91]
	v_mfma_f32_16x16x32_bf16 v[76:79], v[152:155], v[222:225], v[76:79]
	v_mfma_f32_16x16x32_bf16 v[72:75], v[170:173], v[222:225], v[72:75]
	v_mfma_f32_16x16x32_bf16 v[116:119], v[174:177], v[194:197], v[116:119]
	v_mfma_f32_16x16x32_bf16 v[112:115], v[182:185], v[194:197], v[112:115]
	v_mfma_f32_16x16x32_bf16 v[100:103], v[174:177], v[202:205], v[100:103]
	v_mfma_f32_16x16x32_bf16 v[96:99], v[182:185], v[202:205], v[96:99]
	v_mfma_f32_16x16x32_bf16 v[84:87], v[174:177], v[210:213], v[84:87]
	v_mfma_f32_16x16x32_bf16 v[80:83], v[182:185], v[210:213], v[80:83]
	v_mfma_f32_16x16x32_bf16 v[68:71], v[174:177], v[218:221], v[68:71]
	v_mfma_f32_16x16x32_bf16 v[64:67], v[182:185], v[218:221], v[64:67]
	v_mfma_f32_16x16x32_bf16 v[116:119], v[178:181], v[198:201], v[116:119]
	v_mfma_f32_16x16x32_bf16 v[112:115], v[190:193], v[198:201], v[112:115]
	v_mfma_f32_16x16x32_bf16 v[100:103], v[178:181], v[206:209], v[100:103]
	v_mfma_f32_16x16x32_bf16 v[96:99], v[190:193], v[206:209], v[96:99]
	v_mfma_f32_16x16x32_bf16 v[84:87], v[178:181], v[214:217], v[84:87]
	v_mfma_f32_16x16x32_bf16 v[80:83], v[190:193], v[214:217], v[80:83]
	v_mfma_f32_16x16x32_bf16 v[68:71], v[178:181], v[222:225], v[68:71]
	v_mfma_f32_16x16x32_bf16 v[64:67], v[190:193], v[222:225], v[64:67]
	s_barrier
	s_add_i32 s52, s45, s24
	v_lshl_add_u64 v[156:157], s[34:35], 0, v[130:131]
	s_mov_b32 m0, s52
	s_setprio 2
	ds_read_b128 v[194:197], v162 offset:16384
	ds_read_b128 v[198:201], v162 offset:17408
	ds_read_b128 v[202:205], v162 offset:18432
	ds_read_b128 v[206:209], v162 offset:19456
	ds_read_b128 v[210:213], v162 offset:20480
	ds_read_b128 v[214:217], v162 offset:21504
	ds_read_b128 v[218:221], v162 offset:22528
	ds_read_b128 v[222:225], v162 offset:23552
	s_setprio 0
	global_load_lds_dwordx4 v[156:157], off
	s_add_i32 m0, s52, 0x2000
	s_add_u32 s52, s34, 0x20000
	v_lshl_add_u64 v[186:187], s[34:35], 0, v[134:135]
	s_addc_u32 s53, s35, 0
	s_add_i32 s54, s46, s24
	global_load_lds_dwordx4 v[186:187], off
	v_lshl_add_u64 v[226:227], s[52:53], 0, v[130:131]
	s_mov_b32 m0, s54
	v_lshl_add_u64 v[228:229], s[36:37], 0, v[132:133]
	global_load_lds_dwordx4 v[226:227], off
	v_lshl_add_u64 v[226:227], s[52:53], 0, v[134:135]
	s_add_i32 m0, s54, 0x2000
	s_nop 0
	global_load_lds_dwordx4 v[226:227], off
	v_lshl_add_u64 v[226:227], s[36:37], 0, v[128:129]
	s_mov_b32 m0, s9
	s_nop 0
	global_load_lds_dwordx4 v[226:227], off
	s_mov_b32 m0, s25
	s_nop 0
	global_load_lds_dwordx4 v[228:229], off
	s_waitcnt vmcnt(8)
	s_waitcnt lgkmcnt(0)
	s_barrier
	s_waitcnt lgkmcnt(0)
	v_mfma_f32_16x16x32_bf16 v[60:63], v[148:151], v[194:197], v[60:63]
	v_mfma_f32_16x16x32_bf16 v[56:59], v[166:169], v[194:197], v[56:59]
	v_mfma_f32_16x16x32_bf16 v[44:47], v[148:151], v[202:205], v[44:47]
	v_mfma_f32_16x16x32_bf16 v[40:43], v[166:169], v[202:205], v[40:43]
	v_mfma_f32_16x16x32_bf16 v[28:31], v[148:151], v[210:213], v[28:31]
	v_mfma_f32_16x16x32_bf16 v[24:27], v[166:169], v[210:213], v[24:27]
	v_mfma_f32_16x16x32_bf16 v[12:15], v[148:151], v[218:221], v[12:15]
	v_mfma_f32_16x16x32_bf16 v[8:11], v[166:169], v[218:221], v[8:11]
	v_mfma_f32_16x16x32_bf16 v[60:63], v[152:155], v[198:201], v[60:63]
	v_mfma_f32_16x16x32_bf16 v[56:59], v[170:173], v[198:201], v[56:59]
	v_mfma_f32_16x16x32_bf16 v[44:47], v[152:155], v[206:209], v[44:47]
	v_mfma_f32_16x16x32_bf16 v[40:43], v[170:173], v[206:209], v[40:43]
	v_mfma_f32_16x16x32_bf16 v[28:31], v[152:155], v[214:217], v[28:31]
	v_mfma_f32_16x16x32_bf16 v[24:27], v[170:173], v[214:217], v[24:27]
	v_mfma_f32_16x16x32_bf16 v[12:15], v[152:155], v[222:225], v[12:15]
	v_mfma_f32_16x16x32_bf16 v[8:11], v[170:173], v[222:225], v[8:11]
	v_mfma_f32_16x16x32_bf16 v[52:55], v[174:177], v[194:197], v[52:55]
	v_mfma_f32_16x16x32_bf16 v[48:51], v[182:185], v[194:197], v[48:51]
	v_mfma_f32_16x16x32_bf16 v[36:39], v[174:177], v[202:205], v[36:39]
	v_mfma_f32_16x16x32_bf16 v[32:35], v[182:185], v[202:205], v[32:35]
	v_mfma_f32_16x16x32_bf16 v[20:23], v[174:177], v[210:213], v[20:23]
	v_mfma_f32_16x16x32_bf16 v[16:19], v[182:185], v[210:213], v[16:19]
	v_mfma_f32_16x16x32_bf16 v[4:7], v[174:177], v[218:221], v[4:7]
	v_mfma_f32_16x16x32_bf16 v[0:3], v[182:185], v[218:221], v[0:3]
	v_mfma_f32_16x16x32_bf16 v[52:55], v[178:181], v[198:201], v[52:55]
	v_mfma_f32_16x16x32_bf16 v[48:51], v[190:193], v[198:201], v[48:51]
	v_mfma_f32_16x16x32_bf16 v[36:39], v[178:181], v[206:209], v[36:39]
	v_mfma_f32_16x16x32_bf16 v[32:35], v[190:193], v[206:209], v[32:35]
	v_mfma_f32_16x16x32_bf16 v[20:23], v[178:181], v[214:217], v[20:23]
	v_mfma_f32_16x16x32_bf16 v[16:19], v[190:193], v[214:217], v[16:19]
	v_mfma_f32_16x16x32_bf16 v[4:7], v[178:181], v[222:225], v[4:7]
	v_mfma_f32_16x16x32_bf16 v[0:3], v[190:193], v[222:225], v[0:3]
	s_barrier
	s_add_i32 s52, 0, 0x18000
	v_add_u32_e32 v165, s52, v159
	s_add_i32 s53, 0, 0x1c000
	s_setprio 2
	ds_read_b128 v[148:151], v165
	ds_read_b128 v[152:155], v165 offset:1024
	ds_read_b128 v[166:169], v165 offset:2048
	ds_read_b128 v[170:173], v165 offset:3072
	v_add_u32_e32 v165, s53, v159
	ds_read_b128 v[174:177], v165
	ds_read_b128 v[178:181], v165 offset:1024
	ds_read_b128 v[182:185], v165 offset:2048
	ds_read_b128 v[190:193], v165 offset:3072
	s_add_u32 s36, s36, 0x20000
	s_addc_u32 s37, s37, 0
	s_mov_b32 m0, s38
	v_lshl_add_u64 v[230:231], s[36:37], 0, v[128:129]
	ds_read_b128 v[194:197], v162 offset:32768
	ds_read_b128 v[198:201], v162 offset:33792
	ds_read_b128 v[202:205], v162 offset:34816
	ds_read_b128 v[206:209], v162 offset:35840
	ds_read_b128 v[210:213], v162 offset:36864
	ds_read_b128 v[214:217], v162 offset:37888
	ds_read_b128 v[218:221], v162 offset:38912
	ds_read_b128 v[222:225], v162 offset:39936
	s_setprio 0
	global_load_lds_dwordx4 v[230:231], off
	v_lshl_add_u64 v[230:231], s[36:37], 0, v[132:133]
	s_mov_b32 m0, s39
	s_nop 0
	global_load_lds_dwordx4 v[230:231], off
	s_waitcnt vmcnt(8)
	s_waitcnt lgkmcnt(0)
	s_barrier
	s_waitcnt lgkmcnt(0)
	v_mfma_f32_16x16x32_bf16 v[124:127], v[148:151], v[194:197], v[124:127]
	v_mfma_f32_16x16x32_bf16 v[120:123], v[166:169], v[194:197], v[120:123]
	v_mfma_f32_16x16x32_bf16 v[108:111], v[148:151], v[202:205], v[108:111]
	v_mfma_f32_16x16x32_bf16 v[104:107], v[166:169], v[202:205], v[104:107]
	v_mfma_f32_16x16x32_bf16 v[92:95], v[148:151], v[210:213], v[92:95]
	v_mfma_f32_16x16x32_bf16 v[88:91], v[166:169], v[210:213], v[88:91]
	v_mfma_f32_16x16x32_bf16 v[76:79], v[148:151], v[218:221], v[76:79]
	v_mfma_f32_16x16x32_bf16 v[72:75], v[166:169], v[218:221], v[72:75]
	v_mfma_f32_16x16x32_bf16 v[124:127], v[152:155], v[198:201], v[124:127]
	v_mfma_f32_16x16x32_bf16 v[120:123], v[170:173], v[198:201], v[120:123]
	v_mfma_f32_16x16x32_bf16 v[108:111], v[152:155], v[206:209], v[108:111]
	v_mfma_f32_16x16x32_bf16 v[104:107], v[170:173], v[206:209], v[104:107]
	v_mfma_f32_16x16x32_bf16 v[92:95], v[152:155], v[214:217], v[92:95]
	v_mfma_f32_16x16x32_bf16 v[88:91], v[170:173], v[214:217], v[88:91]
	v_mfma_f32_16x16x32_bf16 v[76:79], v[152:155], v[222:225], v[76:79]
	v_mfma_f32_16x16x32_bf16 v[72:75], v[170:173], v[222:225], v[72:75]
	v_mfma_f32_16x16x32_bf16 v[116:119], v[174:177], v[194:197], v[116:119]
	v_mfma_f32_16x16x32_bf16 v[112:115], v[182:185], v[194:197], v[112:115]
	v_mfma_f32_16x16x32_bf16 v[100:103], v[174:177], v[202:205], v[100:103]
	v_mfma_f32_16x16x32_bf16 v[96:99], v[182:185], v[202:205], v[96:99]
	v_mfma_f32_16x16x32_bf16 v[84:87], v[174:177], v[210:213], v[84:87]
	v_mfma_f32_16x16x32_bf16 v[80:83], v[182:185], v[210:213], v[80:83]
	v_mfma_f32_16x16x32_bf16 v[68:71], v[174:177], v[218:221], v[68:71]
	v_mfma_f32_16x16x32_bf16 v[64:67], v[182:185], v[218:221], v[64:67]
	v_mfma_f32_16x16x32_bf16 v[116:119], v[178:181], v[198:201], v[116:119]
	v_mfma_f32_16x16x32_bf16 v[112:115], v[190:193], v[198:201], v[112:115]
	v_mfma_f32_16x16x32_bf16 v[100:103], v[178:181], v[206:209], v[100:103]
	v_mfma_f32_16x16x32_bf16 v[96:99], v[190:193], v[206:209], v[96:99]
	v_mfma_f32_16x16x32_bf16 v[84:87], v[178:181], v[214:217], v[84:87]
	v_mfma_f32_16x16x32_bf16 v[80:83], v[190:193], v[214:217], v[80:83]
	v_mfma_f32_16x16x32_bf16 v[68:71], v[178:181], v[222:225], v[68:71]
	v_mfma_f32_16x16x32_bf16 v[64:67], v[190:193], v[222:225], v[64:67]
	s_barrier
	s_add_i32 s36, s52, s24
	v_lshl_add_u64 v[156:157], v[156:157], 0, s[16:17]
	s_mov_b32 m0, s36
	s_setprio 2
	ds_read_b128 v[194:197], v162 offset:49152
	ds_read_b128 v[198:201], v162 offset:50176
	ds_read_b128 v[202:205], v162 offset:51200
	ds_read_b128 v[206:209], v162 offset:52224
	ds_read_b128 v[210:213], v162 offset:53248
	ds_read_b128 v[214:217], v162 offset:54272
	ds_read_b128 v[218:221], v162 offset:55296
	ds_read_b128 v[222:225], v162 offset:56320
	s_setprio 0
	global_load_lds_dwordx4 v[156:157], off
	s_add_i32 m0, s36, 0x2000
	s_add_u32 s34, s34, 0x20080
	v_lshl_add_u64 v[156:157], v[186:187], 0, s[16:17]
	s_addc_u32 s35, s35, 0
	s_add_i32 s36, s53, s24
	global_load_lds_dwordx4 v[156:157], off
	v_lshl_add_u64 v[156:157], s[34:35], 0, v[130:131]
	s_mov_b32 m0, s36
	s_nop 0
	global_load_lds_dwordx4 v[156:157], off
	v_lshl_add_u64 v[156:157], s[34:35], 0, v[134:135]
	s_add_i32 m0, s36, 0x2000
	s_nop 0
	global_load_lds_dwordx4 v[156:157], off
	v_lshl_add_u64 v[156:157], v[226:227], 0, s[16:17]
	s_mov_b32 m0, s41
	s_nop 0
	global_load_lds_dwordx4 v[156:157], off
	v_lshl_add_u64 v[156:157], v[228:229], 0, s[16:17]
	s_mov_b32 m0, s42
	s_nop 0
	global_load_lds_dwordx4 v[156:157], off
	s_waitcnt vmcnt(8)
	s_waitcnt lgkmcnt(0)
	s_barrier
	s_waitcnt lgkmcnt(0)
	v_mfma_f32_16x16x32_bf16 v[60:63], v[148:151], v[194:197], v[60:63]
	v_mfma_f32_16x16x32_bf16 v[56:59], v[166:169], v[194:197], v[56:59]
	v_mfma_f32_16x16x32_bf16 v[44:47], v[148:151], v[202:205], v[44:47]
	v_mfma_f32_16x16x32_bf16 v[40:43], v[166:169], v[202:205], v[40:43]
	v_mfma_f32_16x16x32_bf16 v[28:31], v[148:151], v[210:213], v[28:31]
	v_mfma_f32_16x16x32_bf16 v[24:27], v[166:169], v[210:213], v[24:27]
	v_mfma_f32_16x16x32_bf16 v[12:15], v[148:151], v[218:221], v[12:15]
	v_mfma_f32_16x16x32_bf16 v[8:11], v[166:169], v[218:221], v[8:11]
	v_mfma_f32_16x16x32_bf16 v[60:63], v[152:155], v[198:201], v[60:63]
	v_mfma_f32_16x16x32_bf16 v[56:59], v[170:173], v[198:201], v[56:59]
	v_mfma_f32_16x16x32_bf16 v[44:47], v[152:155], v[206:209], v[44:47]
	v_mfma_f32_16x16x32_bf16 v[40:43], v[170:173], v[206:209], v[40:43]
	v_mfma_f32_16x16x32_bf16 v[28:31], v[152:155], v[214:217], v[28:31]
	v_mfma_f32_16x16x32_bf16 v[24:27], v[170:173], v[214:217], v[24:27]
	v_mfma_f32_16x16x32_bf16 v[12:15], v[152:155], v[222:225], v[12:15]
	v_mfma_f32_16x16x32_bf16 v[8:11], v[170:173], v[222:225], v[8:11]
	v_mfma_f32_16x16x32_bf16 v[52:55], v[174:177], v[194:197], v[52:55]
	v_mfma_f32_16x16x32_bf16 v[48:51], v[182:185], v[194:197], v[48:51]
	v_mfma_f32_16x16x32_bf16 v[36:39], v[174:177], v[202:205], v[36:39]
	v_mfma_f32_16x16x32_bf16 v[32:35], v[182:185], v[202:205], v[32:35]
	v_mfma_f32_16x16x32_bf16 v[20:23], v[174:177], v[210:213], v[20:23]
	v_mfma_f32_16x16x32_bf16 v[16:19], v[182:185], v[210:213], v[16:19]
	v_mfma_f32_16x16x32_bf16 v[4:7], v[174:177], v[218:221], v[4:7]
	v_mfma_f32_16x16x32_bf16 v[0:3], v[182:185], v[218:221], v[0:3]
	v_mfma_f32_16x16x32_bf16 v[52:55], v[178:181], v[198:201], v[52:55]
	v_mfma_f32_16x16x32_bf16 v[48:51], v[190:193], v[198:201], v[48:51]
	v_mfma_f32_16x16x32_bf16 v[36:39], v[178:181], v[206:209], v[36:39]
	v_mfma_f32_16x16x32_bf16 v[32:35], v[190:193], v[206:209], v[32:35]
	v_mfma_f32_16x16x32_bf16 v[20:23], v[178:181], v[214:217], v[20:23]
	v_mfma_f32_16x16x32_bf16 v[16:19], v[190:193], v[214:217], v[16:19]
	v_mfma_f32_16x16x32_bf16 v[4:7], v[178:181], v[222:225], v[4:7]
	v_mfma_f32_16x16x32_bf16 v[0:3], v[190:193], v[222:225], v[0:3]
	s_barrier
	s_add_i32 s51, s51, 2
	s_add_u32 s10, s10, 0x100
	s_addc_u32 s11, s11, 0
	s_add_u32 s49, s49, 0x100
	s_addc_u32 s50, s50, 0
	s_cmp_gt_u32 s51, 5
	s_cbranch_scc0 .LBB0_1037
	s_and_b64 vcc, exec, s[18:19]
	s_cbranch_vccz .LBB0_1040
	s_barrier

.LBB0_1452:
	s_setprio 2
	ds_read_b128 v[128:131], v177
	ds_read_b128 v[132:135], v177 offset:1024
	ds_read_b128 v[136:139], v177 offset:2048
	ds_read_b128 v[140:143], v177 offset:3072
	ds_read_b128 v[160:163], v178
	ds_read_b128 v[164:167], v178 offset:1024
	ds_read_b128 v[168:171], v178 offset:2048
	ds_read_b128 v[182:185], v178 offset:3072
	s_add_u32 s28, s26, 0xfff80080
	s_addc_u32 s29, s27, -1
	s_cmp_eq_u32 s50, 28
	s_cselect_b32 s31, s15, s29
	s_cselect_b32 s30, s23, s28
	s_cselect_b32 s29, s17, s49
	s_cselect_b32 s28, s25, s48
	v_lshl_add_u64 v[172:173], s[26:27], 0, v[152:153]
	s_add_i32 m0, s34, 0xc000
	ds_read_b128 v[190:193], v179
	ds_read_b128 v[194:197], v179 offset:1024
	ds_read_b128 v[198:201], v179 offset:2048
	ds_read_b128 v[202:205], v179 offset:3072
	ds_read_b128 v[206:209], v179 offset:4096
	ds_read_b128 v[210:213], v179 offset:5120
	ds_read_b128 v[214:217], v179 offset:6144
	ds_read_b128 v[218:221], v179 offset:7168
	s_setprio 0
	global_load_lds_dwordx4 v[172:173], off
	v_lshl_add_u64 v[172:173], s[26:27], 0, v[154:155]
	s_add_i32 m0, s34, 0xe000
	s_nop 0
	global_load_lds_dwordx4 v[172:173], off
	s_waitcnt vmcnt(8)
	s_waitcnt lgkmcnt(0)
	s_barrier
	s_waitcnt lgkmcnt(0)
	v_mfma_f32_16x16x32_bf16 v[124:127], v[128:131], v[190:193], v[124:127]
	v_mfma_f32_16x16x32_bf16 v[120:123], v[136:139], v[190:193], v[120:123]
	v_mfma_f32_16x16x32_bf16 v[108:111], v[128:131], v[198:201], v[108:111]
	v_mfma_f32_16x16x32_bf16 v[104:107], v[136:139], v[198:201], v[104:107]
	v_mfma_f32_16x16x32_bf16 v[92:95], v[128:131], v[206:209], v[92:95]
	v_mfma_f32_16x16x32_bf16 v[88:91], v[136:139], v[206:209], v[88:91]
	v_mfma_f32_16x16x32_bf16 v[76:79], v[128:131], v[214:217], v[76:79]
	v_mfma_f32_16x16x32_bf16 v[72:75], v[136:139], v[214:217], v[72:75]
	v_mfma_f32_16x16x32_bf16 v[124:127], v[132:135], v[194:197], v[124:127]
	v_mfma_f32_16x16x32_bf16 v[120:123], v[140:143], v[194:197], v[120:123]
	v_mfma_f32_16x16x32_bf16 v[108:111], v[132:135], v[202:205], v[108:111]
	v_mfma_f32_16x16x32_bf16 v[104:107], v[140:143], v[202:205], v[104:107]
	v_mfma_f32_16x16x32_bf16 v[92:95], v[132:135], v[210:213], v[92:95]
	v_mfma_f32_16x16x32_bf16 v[88:91], v[140:143], v[210:213], v[88:91]
	v_mfma_f32_16x16x32_bf16 v[76:79], v[132:135], v[218:221], v[76:79]
	v_mfma_f32_16x16x32_bf16 v[72:75], v[140:143], v[218:221], v[72:75]
	v_mfma_f32_16x16x32_bf16 v[116:119], v[160:163], v[190:193], v[116:119]
	v_mfma_f32_16x16x32_bf16 v[112:115], v[168:171], v[190:193], v[112:115]
	v_mfma_f32_16x16x32_bf16 v[100:103], v[160:163], v[198:201], v[100:103]
	v_mfma_f32_16x16x32_bf16 v[96:99], v[168:171], v[198:201], v[96:99]
	v_mfma_f32_16x16x32_bf16 v[84:87], v[160:163], v[206:209], v[84:87]
	v_mfma_f32_16x16x32_bf16 v[80:83], v[168:171], v[206:209], v[80:83]
	v_mfma_f32_16x16x32_bf16 v[68:71], v[160:163], v[214:217], v[68:71]
	v_mfma_f32_16x16x32_bf16 v[64:67], v[168:171], v[214:217], v[64:67]
	v_mfma_f32_16x16x32_bf16 v[116:119], v[164:167], v[194:197], v[116:119]
	v_mfma_f32_16x16x32_bf16 v[112:115], v[182:185], v[194:197], v[112:115]
	v_mfma_f32_16x16x32_bf16 v[100:103], v[164:167], v[202:205], v[100:103]
	v_mfma_f32_16x16x32_bf16 v[96:99], v[182:185], v[202:205], v[96:99]
	v_mfma_f32_16x16x32_bf16 v[84:87], v[164:167], v[210:213], v[84:87]
	v_mfma_f32_16x16x32_bf16 v[80:83], v[182:185], v[210:213], v[80:83]
	v_mfma_f32_16x16x32_bf16 v[68:71], v[164:167], v[218:221], v[68:71]
	v_mfma_f32_16x16x32_bf16 v[64:67], v[182:185], v[218:221], v[64:67]
	s_barrier
	s_add_i32 s51, s45, s33
	v_lshl_add_u64 v[172:173], s[28:29], 0, v[146:147]
	s_mov_b32 m0, s51
	s_setprio 2
	ds_read_b128 v[190:193], v179 offset:16384
	ds_read_b128 v[194:197], v179 offset:17408
	ds_read_b128 v[198:201], v179 offset:18432
	ds_read_b128 v[202:205], v179 offset:19456
	ds_read_b128 v[206:209], v179 offset:20480
	ds_read_b128 v[210:213], v179 offset:21504
	ds_read_b128 v[214:217], v179 offset:22528
	ds_read_b128 v[218:221], v179 offset:23552
	s_setprio 0
	global_load_lds_dwordx4 v[172:173], off
	s_add_i32 m0, s51, 0x2000
	s_add_u32 s52, s28, 0x80000
	v_lshl_add_u64 v[186:187], s[28:29], 0, v[150:151]
	s_addc_u32 s53, s29, 0
	s_add_i32 s51, s46, s33
	global_load_lds_dwordx4 v[186:187], off
	v_lshl_add_u64 v[222:223], s[52:53], 0, v[146:147]
	s_mov_b32 m0, s51
	v_lshl_add_u64 v[224:225], s[30:31], 0, v[148:149]
	global_load_lds_dwordx4 v[222:223], off
	v_lshl_add_u64 v[222:223], s[52:53], 0, v[150:151]
	s_add_i32 m0, s51, 0x2000
	s_nop 0
	global_load_lds_dwordx4 v[222:223], off
	v_lshl_add_u64 v[222:223], s[30:31], 0, v[144:145]
	s_mov_b32 m0, s34
	s_nop 0
	global_load_lds_dwordx4 v[222:223], off
	s_mov_b32 m0, s35
	s_nop 0
	global_load_lds_dwordx4 v[224:225], off
	s_waitcnt vmcnt(8)
	s_waitcnt lgkmcnt(0)
	s_barrier
	s_waitcnt lgkmcnt(0)
	v_mfma_f32_16x16x32_bf16 v[60:63], v[128:131], v[190:193], v[60:63]
	v_mfma_f32_16x16x32_bf16 v[56:59], v[136:139], v[190:193], v[56:59]
	v_mfma_f32_16x16x32_bf16 v[44:47], v[128:131], v[198:201], v[44:47]
	v_mfma_f32_16x16x32_bf16 v[40:43], v[136:139], v[198:201], v[40:43]
	v_mfma_f32_16x16x32_bf16 v[28:31], v[128:131], v[206:209], v[28:31]
	v_mfma_f32_16x16x32_bf16 v[24:27], v[136:139], v[206:209], v[24:27]
	v_mfma_f32_16x16x32_bf16 v[12:15], v[128:131], v[214:217], v[12:15]
	v_mfma_f32_16x16x32_bf16 v[8:11], v[136:139], v[214:217], v[8:11]
	v_mfma_f32_16x16x32_bf16 v[60:63], v[132:135], v[194:197], v[60:63]
	v_mfma_f32_16x16x32_bf16 v[56:59], v[140:143], v[194:197], v[56:59]
	v_mfma_f32_16x16x32_bf16 v[44:47], v[132:135], v[202:205], v[44:47]
	v_mfma_f32_16x16x32_bf16 v[40:43], v[140:143], v[202:205], v[40:43]
	v_mfma_f32_16x16x32_bf16 v[28:31], v[132:135], v[210:213], v[28:31]
	v_mfma_f32_16x16x32_bf16 v[24:27], v[140:143], v[210:213], v[24:27]
	v_mfma_f32_16x16x32_bf16 v[12:15], v[132:135], v[218:221], v[12:15]
	v_mfma_f32_16x16x32_bf16 v[8:11], v[140:143], v[218:221], v[8:11]
	v_mfma_f32_16x16x32_bf16 v[52:55], v[160:163], v[190:193], v[52:55]
	v_mfma_f32_16x16x32_bf16 v[48:51], v[168:171], v[190:193], v[48:51]
	v_mfma_f32_16x16x32_bf16 v[36:39], v[160:163], v[198:201], v[36:39]
	v_mfma_f32_16x16x32_bf16 v[32:35], v[168:171], v[198:201], v[32:35]
	v_mfma_f32_16x16x32_bf16 v[20:23], v[160:163], v[206:209], v[20:23]
	v_mfma_f32_16x16x32_bf16 v[16:19], v[168:171], v[206:209], v[16:19]
	v_mfma_f32_16x16x32_bf16 v[4:7], v[160:163], v[214:217], v[4:7]
	v_mfma_f32_16x16x32_bf16 v[0:3], v[168:171], v[214:217], v[0:3]
	v_mfma_f32_16x16x32_bf16 v[52:55], v[164:167], v[194:197], v[52:55]
	v_mfma_f32_16x16x32_bf16 v[48:51], v[182:185], v[194:197], v[48:51]
	v_mfma_f32_16x16x32_bf16 v[36:39], v[164:167], v[202:205], v[36:39]
	v_mfma_f32_16x16x32_bf16 v[32:35], v[182:185], v[202:205], v[32:35]
	v_mfma_f32_16x16x32_bf16 v[20:23], v[164:167], v[210:213], v[20:23]
	v_mfma_f32_16x16x32_bf16 v[16:19], v[182:185], v[210:213], v[16:19]
	v_mfma_f32_16x16x32_bf16 v[4:7], v[164:167], v[218:221], v[4:7]
	v_mfma_f32_16x16x32_bf16 v[0:3], v[182:185], v[218:221], v[0:3]
	s_barrier
	s_add_i32 s51, 0, 0x18000
	s_add_i32 s52, 0, 0x1c000
	v_add_u32_e32 v140, s51, v175
	v_add_u32_e32 v181, s52, v175
	s_setprio 2
	ds_read_b128 v[128:131], v140
	ds_read_b128 v[132:135], v140 offset:1024
	ds_read_b128 v[136:139], v140 offset:2048
	ds_read_b128 v[140:143], v140 offset:3072
	ds_read_b128 v[160:163], v181
	ds_read_b128 v[164:167], v181 offset:1024
	ds_read_b128 v[168:171], v181 offset:2048
	ds_read_b128 v[182:185], v181 offset:3072
	s_add_u32 s30, s30, 0x80000
	s_addc_u32 s31, s31, 0
	s_mov_b32 m0, s36
	v_lshl_add_u64 v[226:227], s[30:31], 0, v[144:145]
	ds_read_b128 v[190:193], v179 offset:32768
	ds_read_b128 v[194:197], v179 offset:33792
	ds_read_b128 v[198:201], v179 offset:34816
	ds_read_b128 v[202:205], v179 offset:35840
	ds_read_b128 v[206:209], v179 offset:36864
	ds_read_b128 v[210:213], v179 offset:37888
	ds_read_b128 v[214:217], v179 offset:38912
	ds_read_b128 v[218:221], v179 offset:39936
	s_setprio 0
	global_load_lds_dwordx4 v[226:227], off
	v_lshl_add_u64 v[226:227], s[30:31], 0, v[148:149]
	s_mov_b32 m0, s37
	s_nop 0
	global_load_lds_dwordx4 v[226:227], off
	s_waitcnt vmcnt(8)
	s_waitcnt lgkmcnt(0)
	s_barrier
	s_waitcnt lgkmcnt(0)
	v_mfma_f32_16x16x32_bf16 v[124:127], v[128:131], v[190:193], v[124:127]
	v_mfma_f32_16x16x32_bf16 v[120:123], v[136:139], v[190:193], v[120:123]
	v_mfma_f32_16x16x32_bf16 v[108:111], v[128:131], v[198:201], v[108:111]
	v_mfma_f32_16x16x32_bf16 v[104:107], v[136:139], v[198:201], v[104:107]
	v_mfma_f32_16x16x32_bf16 v[92:95], v[128:131], v[206:209], v[92:95]
	v_mfma_f32_16x16x32_bf16 v[88:91], v[136:139], v[206:209], v[88:91]
	v_mfma_f32_16x16x32_bf16 v[76:79], v[128:131], v[214:217], v[76:79]
	v_mfma_f32_16x16x32_bf16 v[72:75], v[136:139], v[214:217], v[72:75]
	v_mfma_f32_16x16x32_bf16 v[124:127], v[132:135], v[194:197], v[124:127]
	v_mfma_f32_16x16x32_bf16 v[120:123], v[140:143], v[194:197], v[120:123]
	v_mfma_f32_16x16x32_bf16 v[108:111], v[132:135], v[202:205], v[108:111]
	v_mfma_f32_16x16x32_bf16 v[104:107], v[140:143], v[202:205], v[104:107]
	v_mfma_f32_16x16x32_bf16 v[92:95], v[132:135], v[210:213], v[92:95]
	v_mfma_f32_16x16x32_bf16 v[88:91], v[140:143], v[210:213], v[88:91]
	v_mfma_f32_16x16x32_bf16 v[76:79], v[132:135], v[218:221], v[76:79]
	v_mfma_f32_16x16x32_bf16 v[72:75], v[140:143], v[218:221], v[72:75]
	v_mfma_f32_16x16x32_bf16 v[116:119], v[160:163], v[190:193], v[116:119]
	v_mfma_f32_16x16x32_bf16 v[112:115], v[168:171], v[190:193], v[112:115]
	v_mfma_f32_16x16x32_bf16 v[100:103], v[160:163], v[198:201], v[100:103]
	v_mfma_f32_16x16x32_bf16 v[96:99], v[168:171], v[198:201], v[96:99]
	v_mfma_f32_16x16x32_bf16 v[84:87], v[160:163], v[206:209], v[84:87]
	v_mfma_f32_16x16x32_bf16 v[80:83], v[168:171], v[206:209], v[80:83]
	v_mfma_f32_16x16x32_bf16 v[68:71], v[160:163], v[214:217], v[68:71]
	v_mfma_f32_16x16x32_bf16 v[64:67], v[168:171], v[214:217], v[64:67]
	v_mfma_f32_16x16x32_bf16 v[116:119], v[164:167], v[194:197], v[116:119]
	v_mfma_f32_16x16x32_bf16 v[112:115], v[182:185], v[194:197], v[112:115]
	v_mfma_f32_16x16x32_bf16 v[100:103], v[164:167], v[202:205], v[100:103]
	v_mfma_f32_16x16x32_bf16 v[96:99], v[182:185], v[202:205], v[96:99]
	v_mfma_f32_16x16x32_bf16 v[84:87], v[164:167], v[210:213], v[84:87]
	v_mfma_f32_16x16x32_bf16 v[80:83], v[182:185], v[210:213], v[80:83]
	v_mfma_f32_16x16x32_bf16 v[68:71], v[164:167], v[218:221], v[68:71]
	v_mfma_f32_16x16x32_bf16 v[64:67], v[182:185], v[218:221], v[64:67]
	s_barrier
	s_add_i32 s30, s51, s33
	v_lshl_add_u64 v[172:173], v[172:173], 0, s[8:9]
	s_mov_b32 m0, s30
	s_setprio 2
	ds_read_b128 v[190:193], v179 offset:49152
	ds_read_b128 v[194:197], v179 offset:50176
	ds_read_b128 v[198:201], v179 offset:51200
	ds_read_b128 v[202:205], v179 offset:52224
	ds_read_b128 v[206:209], v179 offset:53248
	ds_read_b128 v[210:213], v179 offset:54272
	ds_read_b128 v[214:217], v179 offset:55296
	ds_read_b128 v[218:221], v179 offset:56320
	s_setprio 0
	global_load_lds_dwordx4 v[172:173], off
	s_add_i32 m0, s30, 0x2000
	s_add_u32 s28, s28, 0x80080
	v_lshl_add_u64 v[172:173], v[186:187], 0, s[8:9]
	s_addc_u32 s29, s29, 0
	s_add_i32 s30, s52, s33
	global_load_lds_dwordx4 v[172:173], off
	v_lshl_add_u64 v[172:173], s[28:29], 0, v[146:147]
	s_mov_b32 m0, s30
	s_nop 0
	global_load_lds_dwordx4 v[172:173], off
	v_lshl_add_u64 v[172:173], s[28:29], 0, v[150:151]
	s_add_i32 m0, s30, 0x2000
	s_nop 0
	global_load_lds_dwordx4 v[172:173], off
	v_lshl_add_u64 v[172:173], v[222:223], 0, s[8:9]
	s_mov_b32 m0, s41
	s_nop 0
	global_load_lds_dwordx4 v[172:173], off
	v_lshl_add_u64 v[172:173], v[224:225], 0, s[8:9]
	s_mov_b32 m0, s42
	s_nop 0
	global_load_lds_dwordx4 v[172:173], off
	s_waitcnt vmcnt(8)
	s_waitcnt lgkmcnt(0)
	s_barrier
	s_waitcnt lgkmcnt(0)
	v_mfma_f32_16x16x32_bf16 v[60:63], v[128:131], v[190:193], v[60:63]
	v_mfma_f32_16x16x32_bf16 v[56:59], v[136:139], v[190:193], v[56:59]
	v_mfma_f32_16x16x32_bf16 v[44:47], v[128:131], v[198:201], v[44:47]
	v_mfma_f32_16x16x32_bf16 v[40:43], v[136:139], v[198:201], v[40:43]
	v_mfma_f32_16x16x32_bf16 v[28:31], v[128:131], v[206:209], v[28:31]
	v_mfma_f32_16x16x32_bf16 v[24:27], v[136:139], v[206:209], v[24:27]
	v_mfma_f32_16x16x32_bf16 v[12:15], v[128:131], v[214:217], v[12:15]
	v_mfma_f32_16x16x32_bf16 v[8:11], v[136:139], v[214:217], v[8:11]
	v_mfma_f32_16x16x32_bf16 v[60:63], v[132:135], v[194:197], v[60:63]
	v_mfma_f32_16x16x32_bf16 v[56:59], v[140:143], v[194:197], v[56:59]
	v_mfma_f32_16x16x32_bf16 v[44:47], v[132:135], v[202:205], v[44:47]
	v_mfma_f32_16x16x32_bf16 v[40:43], v[140:143], v[202:205], v[40:43]
	v_mfma_f32_16x16x32_bf16 v[28:31], v[132:135], v[210:213], v[28:31]
	v_mfma_f32_16x16x32_bf16 v[24:27], v[140:143], v[210:213], v[24:27]
	v_mfma_f32_16x16x32_bf16 v[12:15], v[132:135], v[218:221], v[12:15]
	v_mfma_f32_16x16x32_bf16 v[8:11], v[140:143], v[218:221], v[8:11]
	v_mfma_f32_16x16x32_bf16 v[52:55], v[160:163], v[190:193], v[52:55]
	v_mfma_f32_16x16x32_bf16 v[48:51], v[168:171], v[190:193], v[48:51]
	v_mfma_f32_16x16x32_bf16 v[36:39], v[160:163], v[198:201], v[36:39]
	v_mfma_f32_16x16x32_bf16 v[32:35], v[168:171], v[198:201], v[32:35]
	v_mfma_f32_16x16x32_bf16 v[20:23], v[160:163], v[206:209], v[20:23]
	v_mfma_f32_16x16x32_bf16 v[16:19], v[168:171], v[206:209], v[16:19]
	v_mfma_f32_16x16x32_bf16 v[4:7], v[160:163], v[214:217], v[4:7]
	v_mfma_f32_16x16x32_bf16 v[0:3], v[168:171], v[214:217], v[0:3]
	v_mfma_f32_16x16x32_bf16 v[52:55], v[164:167], v[194:197], v[52:55]
	v_mfma_f32_16x16x32_bf16 v[48:51], v[182:185], v[194:197], v[48:51]
	v_mfma_f32_16x16x32_bf16 v[36:39], v[164:167], v[202:205], v[36:39]
	v_mfma_f32_16x16x32_bf16 v[32:35], v[182:185], v[202:205], v[32:35]
	v_mfma_f32_16x16x32_bf16 v[20:23], v[164:167], v[210:213], v[20:23]
	v_mfma_f32_16x16x32_bf16 v[16:19], v[182:185], v[210:213], v[16:19]
	v_mfma_f32_16x16x32_bf16 v[4:7], v[164:167], v[218:221], v[4:7]
	v_mfma_f32_16x16x32_bf16 v[0:3], v[182:185], v[218:221], v[0:3]
	s_barrier
	s_add_i32 s50, s50, 2
	s_add_u32 s26, s26, 0x100
	s_addc_u32 s27, s27, 0
	s_add_u32 s48, s48, 0x100
	s_addc_u32 s49, s49, 0
	s_cmp_gt_u32 s50, 29
	s_cbranch_scc0 .LBB0_1452
	s_and_b64 vcc, exec, s[10:11]
	s_cbranch_vccz .LBB0_1455
	s_barrier

.LBB0_1539:
	s_setprio 2
	ds_read_b128 v[156:159], v151
	ds_read_b128 v[160:163], v151 offset:1024
	ds_read_b128 v[164:167], v151 offset:2048
	ds_read_b128 v[168:171], v151 offset:3072
	ds_read_b128 v[172:175], v152
	ds_read_b128 v[176:179], v152 offset:1024
	ds_read_b128 v[180:183], v152 offset:2048
	ds_read_b128 v[184:187], v152 offset:3072
	s_add_u32 s22, s20, 0xfff80080
	s_addc_u32 s23, s21, -1
	s_cmp_eq_u32 s48, 28
	s_cselect_b32 s25, s11, s23
	s_cselect_b32 s24, s44, s22
	s_cselect_b32 s23, s13, s47
	s_cselect_b32 s22, s45, s46
	v_lshl_add_u64 v[146:147], s[20:21], 0, v[138:139]
	s_add_i32 m0, s19, 0xc000
	ds_read_b128 v[190:193], v153
	ds_read_b128 v[194:197], v153 offset:1024
	ds_read_b128 v[198:201], v153 offset:2048
	ds_read_b128 v[202:205], v153 offset:3072
	ds_read_b128 v[206:209], v153 offset:4096
	ds_read_b128 v[210:213], v153 offset:5120
	ds_read_b128 v[214:217], v153 offset:6144
	ds_read_b128 v[218:221], v153 offset:7168
	s_setprio 0
	global_load_lds_dwordx4 v[146:147], off
	v_lshl_add_u64 v[146:147], s[20:21], 0, v[140:141]
	s_add_i32 m0, s19, 0xe000
	s_nop 0
	global_load_lds_dwordx4 v[146:147], off
	s_waitcnt vmcnt(8)
	s_waitcnt lgkmcnt(0)
	s_barrier
	s_waitcnt lgkmcnt(0)
	v_mfma_f32_16x16x32_bf16 v[116:119], v[156:159], v[190:193], v[116:119]
	v_mfma_f32_16x16x32_bf16 v[112:115], v[164:167], v[190:193], v[112:115]
	v_mfma_f32_16x16x32_bf16 v[100:103], v[156:159], v[198:201], v[100:103]
	v_mfma_f32_16x16x32_bf16 v[96:99], v[164:167], v[198:201], v[96:99]
	v_mfma_f32_16x16x32_bf16 v[84:87], v[156:159], v[206:209], v[84:87]
	v_mfma_f32_16x16x32_bf16 v[80:83], v[164:167], v[206:209], v[80:83]
	v_mfma_f32_16x16x32_bf16 v[68:71], v[156:159], v[214:217], v[68:71]
	v_mfma_f32_16x16x32_bf16 v[64:67], v[164:167], v[214:217], v[64:67]
	v_mfma_f32_16x16x32_bf16 v[116:119], v[160:163], v[194:197], v[116:119]
	v_mfma_f32_16x16x32_bf16 v[112:115], v[168:171], v[194:197], v[112:115]
	v_mfma_f32_16x16x32_bf16 v[100:103], v[160:163], v[202:205], v[100:103]
	v_mfma_f32_16x16x32_bf16 v[96:99], v[168:171], v[202:205], v[96:99]
	v_mfma_f32_16x16x32_bf16 v[84:87], v[160:163], v[210:213], v[84:87]
	v_mfma_f32_16x16x32_bf16 v[80:83], v[168:171], v[210:213], v[80:83]
	v_mfma_f32_16x16x32_bf16 v[68:71], v[160:163], v[218:221], v[68:71]
	v_mfma_f32_16x16x32_bf16 v[64:67], v[168:171], v[218:221], v[64:67]
	v_mfma_f32_16x16x32_bf16 v[124:127], v[172:175], v[190:193], v[124:127]
	v_mfma_f32_16x16x32_bf16 v[120:123], v[180:183], v[190:193], v[120:123]
	v_mfma_f32_16x16x32_bf16 v[108:111], v[172:175], v[198:201], v[108:111]
	v_mfma_f32_16x16x32_bf16 v[104:107], v[180:183], v[198:201], v[104:107]
	v_mfma_f32_16x16x32_bf16 v[92:95], v[172:175], v[206:209], v[92:95]
	v_mfma_f32_16x16x32_bf16 v[88:91], v[180:183], v[206:209], v[88:91]
	v_mfma_f32_16x16x32_bf16 v[76:79], v[172:175], v[214:217], v[76:79]
	v_mfma_f32_16x16x32_bf16 v[72:75], v[180:183], v[214:217], v[72:75]
	v_mfma_f32_16x16x32_bf16 v[124:127], v[176:179], v[194:197], v[124:127]
	v_mfma_f32_16x16x32_bf16 v[120:123], v[184:187], v[194:197], v[120:123]
	v_mfma_f32_16x16x32_bf16 v[108:111], v[176:179], v[202:205], v[108:111]
	v_mfma_f32_16x16x32_bf16 v[104:107], v[184:187], v[202:205], v[104:107]
	v_mfma_f32_16x16x32_bf16 v[92:95], v[176:179], v[210:213], v[92:95]
	v_mfma_f32_16x16x32_bf16 v[88:91], v[184:187], v[210:213], v[88:91]
	v_mfma_f32_16x16x32_bf16 v[76:79], v[176:179], v[218:221], v[76:79]
	v_mfma_f32_16x16x32_bf16 v[72:75], v[184:187], v[218:221], v[72:75]
	s_barrier
	s_add_i32 s49, s40, s28
	v_lshl_add_u64 v[146:147], s[22:23], 0, v[132:133]
	s_mov_b32 m0, s49
	s_setprio 2
	ds_read_b128 v[190:193], v153 offset:16384
	ds_read_b128 v[194:197], v153 offset:17408
	ds_read_b128 v[198:201], v153 offset:18432
	ds_read_b128 v[202:205], v153 offset:19456
	ds_read_b128 v[206:209], v153 offset:20480
	ds_read_b128 v[210:213], v153 offset:21504
	ds_read_b128 v[214:217], v153 offset:22528
	ds_read_b128 v[218:221], v153 offset:23552
	s_setprio 0
	global_load_lds_dwordx4 v[146:147], off
	s_add_i32 m0, s49, 0x2000
	s_add_u32 s50, s22, 0x80000
	v_lshl_add_u64 v[222:223], s[22:23], 0, v[128:129]
	s_addc_u32 s51, s23, 0
	s_add_i32 s49, s41, s28
	global_load_lds_dwordx4 v[222:223], off
	v_lshl_add_u64 v[224:225], s[50:51], 0, v[132:133]
	s_mov_b32 m0, s49
	v_lshl_add_u64 v[226:227], s[24:25], 0, v[130:131]
	global_load_lds_dwordx4 v[224:225], off
	v_lshl_add_u64 v[224:225], s[50:51], 0, v[128:129]
	s_add_i32 m0, s49, 0x2000
	s_nop 0
	global_load_lds_dwordx4 v[224:225], off
	v_lshl_add_u64 v[224:225], s[24:25], 0, v[134:135]
	s_mov_b32 m0, s19
	s_nop 0
	global_load_lds_dwordx4 v[224:225], off
	s_mov_b32 m0, s30
	s_nop 0
	global_load_lds_dwordx4 v[226:227], off
	s_waitcnt vmcnt(8)
	s_waitcnt lgkmcnt(0)
	s_barrier
	s_waitcnt lgkmcnt(0)
	v_mfma_f32_16x16x32_bf16 v[52:55], v[156:159], v[190:193], v[52:55]
	v_mfma_f32_16x16x32_bf16 v[48:51], v[164:167], v[190:193], v[48:51]
	v_mfma_f32_16x16x32_bf16 v[36:39], v[156:159], v[198:201], v[36:39]
	v_mfma_f32_16x16x32_bf16 v[32:35], v[164:167], v[198:201], v[32:35]
	v_mfma_f32_16x16x32_bf16 v[20:23], v[156:159], v[206:209], v[20:23]
	v_mfma_f32_16x16x32_bf16 v[16:19], v[164:167], v[206:209], v[16:19]
	v_mfma_f32_16x16x32_bf16 v[8:11], v[156:159], v[214:217], v[8:11]
	v_mfma_f32_16x16x32_bf16 v[0:3], v[164:167], v[214:217], v[0:3]
	v_mfma_f32_16x16x32_bf16 v[52:55], v[160:163], v[194:197], v[52:55]
	v_mfma_f32_16x16x32_bf16 v[48:51], v[168:171], v[194:197], v[48:51]
	v_mfma_f32_16x16x32_bf16 v[36:39], v[160:163], v[202:205], v[36:39]
	v_mfma_f32_16x16x32_bf16 v[32:35], v[168:171], v[202:205], v[32:35]
	v_mfma_f32_16x16x32_bf16 v[20:23], v[160:163], v[210:213], v[20:23]
	v_mfma_f32_16x16x32_bf16 v[16:19], v[168:171], v[210:213], v[16:19]
	v_mfma_f32_16x16x32_bf16 v[8:11], v[160:163], v[218:221], v[8:11]
	v_mfma_f32_16x16x32_bf16 v[0:3], v[168:171], v[218:221], v[0:3]
	v_mfma_f32_16x16x32_bf16 v[60:63], v[172:175], v[190:193], v[60:63]
	v_mfma_f32_16x16x32_bf16 v[56:59], v[180:183], v[190:193], v[56:59]
	v_mfma_f32_16x16x32_bf16 v[44:47], v[172:175], v[198:201], v[44:47]
	v_mfma_f32_16x16x32_bf16 v[40:43], v[180:183], v[198:201], v[40:43]
	v_mfma_f32_16x16x32_bf16 v[28:31], v[172:175], v[206:209], v[28:31]
	v_mfma_f32_16x16x32_bf16 v[24:27], v[180:183], v[206:209], v[24:27]
	v_mfma_f32_16x16x32_bf16 v[12:15], v[172:175], v[214:217], v[12:15]
	v_mfma_f32_16x16x32_bf16 v[4:7], v[180:183], v[214:217], v[4:7]
	v_mfma_f32_16x16x32_bf16 v[60:63], v[176:179], v[194:197], v[60:63]
	v_mfma_f32_16x16x32_bf16 v[56:59], v[184:187], v[194:197], v[56:59]
	v_mfma_f32_16x16x32_bf16 v[44:47], v[176:179], v[202:205], v[44:47]
	v_mfma_f32_16x16x32_bf16 v[40:43], v[184:187], v[202:205], v[40:43]
	v_mfma_f32_16x16x32_bf16 v[28:31], v[176:179], v[210:213], v[28:31]
	v_mfma_f32_16x16x32_bf16 v[24:27], v[184:187], v[210:213], v[24:27]
	v_mfma_f32_16x16x32_bf16 v[12:15], v[176:179], v[218:221], v[12:15]
	v_mfma_f32_16x16x32_bf16 v[4:7], v[184:187], v[218:221], v[4:7]
	s_barrier
	s_add_i32 s49, 0, 0x18000
	s_add_i32 s50, 0, 0x1c000
	v_add_u32_e32 v168, s49, v149
	v_add_u32_e32 v184, s50, v149
	s_setprio 2
	ds_read_b128 v[156:159], v168
	ds_read_b128 v[160:163], v168 offset:1024
	ds_read_b128 v[164:167], v168 offset:2048
	ds_read_b128 v[168:171], v168 offset:3072
	ds_read_b128 v[172:175], v184
	ds_read_b128 v[176:179], v184 offset:1024
	ds_read_b128 v[180:183], v184 offset:2048
	ds_read_b128 v[184:187], v184 offset:3072
	s_add_u32 s24, s24, 0x80000
	s_addc_u32 s25, s25, 0
	s_mov_b32 m0, s31
	v_lshl_add_u64 v[228:229], s[24:25], 0, v[134:135]
	ds_read_b128 v[190:193], v153 offset:32768
	ds_read_b128 v[194:197], v153 offset:33792
	ds_read_b128 v[198:201], v153 offset:34816
	ds_read_b128 v[202:205], v153 offset:35840
	ds_read_b128 v[206:209], v153 offset:36864
	ds_read_b128 v[210:213], v153 offset:37888
	ds_read_b128 v[214:217], v153 offset:38912
	ds_read_b128 v[218:221], v153 offset:39936
	s_setprio 0
	global_load_lds_dwordx4 v[228:229], off
	v_lshl_add_u64 v[228:229], s[24:25], 0, v[130:131]
	s_mov_b32 m0, s33
	s_nop 0
	global_load_lds_dwordx4 v[228:229], off
	s_waitcnt vmcnt(8)
	s_waitcnt lgkmcnt(0)
	s_barrier
	s_waitcnt lgkmcnt(0)
	v_mfma_f32_16x16x32_bf16 v[116:119], v[156:159], v[190:193], v[116:119]
	v_mfma_f32_16x16x32_bf16 v[112:115], v[164:167], v[190:193], v[112:115]
	v_mfma_f32_16x16x32_bf16 v[100:103], v[156:159], v[198:201], v[100:103]
	v_mfma_f32_16x16x32_bf16 v[96:99], v[164:167], v[198:201], v[96:99]
	v_mfma_f32_16x16x32_bf16 v[84:87], v[156:159], v[206:209], v[84:87]
	v_mfma_f32_16x16x32_bf16 v[80:83], v[164:167], v[206:209], v[80:83]
	v_mfma_f32_16x16x32_bf16 v[68:71], v[156:159], v[214:217], v[68:71]
	v_mfma_f32_16x16x32_bf16 v[64:67], v[164:167], v[214:217], v[64:67]
	v_mfma_f32_16x16x32_bf16 v[116:119], v[160:163], v[194:197], v[116:119]
	v_mfma_f32_16x16x32_bf16 v[112:115], v[168:171], v[194:197], v[112:115]
	v_mfma_f32_16x16x32_bf16 v[100:103], v[160:163], v[202:205], v[100:103]
	v_mfma_f32_16x16x32_bf16 v[96:99], v[168:171], v[202:205], v[96:99]
	v_mfma_f32_16x16x32_bf16 v[84:87], v[160:163], v[210:213], v[84:87]
	v_mfma_f32_16x16x32_bf16 v[80:83], v[168:171], v[210:213], v[80:83]
	v_mfma_f32_16x16x32_bf16 v[68:71], v[160:163], v[218:221], v[68:71]
	v_mfma_f32_16x16x32_bf16 v[64:67], v[168:171], v[218:221], v[64:67]
	v_mfma_f32_16x16x32_bf16 v[124:127], v[172:175], v[190:193], v[124:127]
	v_mfma_f32_16x16x32_bf16 v[120:123], v[180:183], v[190:193], v[120:123]
	v_mfma_f32_16x16x32_bf16 v[108:111], v[172:175], v[198:201], v[108:111]
	v_mfma_f32_16x16x32_bf16 v[104:107], v[180:183], v[198:201], v[104:107]
	v_mfma_f32_16x16x32_bf16 v[92:95], v[172:175], v[206:209], v[92:95]
	v_mfma_f32_16x16x32_bf16 v[88:91], v[180:183], v[206:209], v[88:91]
	v_mfma_f32_16x16x32_bf16 v[76:79], v[172:175], v[214:217], v[76:79]
	v_mfma_f32_16x16x32_bf16 v[72:75], v[180:183], v[214:217], v[72:75]
	v_mfma_f32_16x16x32_bf16 v[124:127], v[176:179], v[194:197], v[124:127]
	v_mfma_f32_16x16x32_bf16 v[120:123], v[184:187], v[194:197], v[120:123]
	v_mfma_f32_16x16x32_bf16 v[108:111], v[176:179], v[202:205], v[108:111]
	v_mfma_f32_16x16x32_bf16 v[104:107], v[184:187], v[202:205], v[104:107]
	v_mfma_f32_16x16x32_bf16 v[92:95], v[176:179], v[210:213], v[92:95]
	v_mfma_f32_16x16x32_bf16 v[88:91], v[184:187], v[210:213], v[88:91]
	v_mfma_f32_16x16x32_bf16 v[76:79], v[176:179], v[218:221], v[76:79]
	v_mfma_f32_16x16x32_bf16 v[72:75], v[184:187], v[218:221], v[72:75]
	s_barrier
	s_add_i32 s24, s49, s28
	v_lshl_add_u64 v[146:147], v[146:147], 0, s[6:7]
	s_mov_b32 m0, s24
	s_setprio 2
	ds_read_b128 v[190:193], v153 offset:49152
	ds_read_b128 v[194:197], v153 offset:50176
	ds_read_b128 v[198:201], v153 offset:51200
	ds_read_b128 v[202:205], v153 offset:52224
	ds_read_b128 v[206:209], v153 offset:53248
	ds_read_b128 v[210:213], v153 offset:54272
	ds_read_b128 v[214:217], v153 offset:55296
	ds_read_b128 v[218:221], v153 offset:56320
	s_setprio 0
	global_load_lds_dwordx4 v[146:147], off
	s_add_i32 m0, s24, 0x2000
	s_add_u32 s22, s22, 0x80080
	v_lshl_add_u64 v[146:147], v[222:223], 0, s[6:7]
	s_addc_u32 s23, s23, 0
	s_add_i32 s24, s50, s28
	global_load_lds_dwordx4 v[146:147], off
	v_lshl_add_u64 v[146:147], s[22:23], 0, v[132:133]
	s_mov_b32 m0, s24
	s_nop 0
	global_load_lds_dwordx4 v[146:147], off
	v_lshl_add_u64 v[146:147], s[22:23], 0, v[128:129]
	s_add_i32 m0, s24, 0x2000
	s_nop 0
	global_load_lds_dwordx4 v[146:147], off
	v_lshl_add_u64 v[146:147], v[224:225], 0, s[6:7]
	s_mov_b32 m0, s36
	s_nop 0
	global_load_lds_dwordx4 v[146:147], off
	v_lshl_add_u64 v[146:147], v[226:227], 0, s[6:7]
	s_mov_b32 m0, s37
	s_nop 0
	global_load_lds_dwordx4 v[146:147], off
	s_waitcnt vmcnt(8)
	s_waitcnt lgkmcnt(0)
	s_barrier
	s_waitcnt lgkmcnt(0)
	v_mfma_f32_16x16x32_bf16 v[52:55], v[156:159], v[190:193], v[52:55]
	v_mfma_f32_16x16x32_bf16 v[48:51], v[164:167], v[190:193], v[48:51]
	v_mfma_f32_16x16x32_bf16 v[36:39], v[156:159], v[198:201], v[36:39]
	v_mfma_f32_16x16x32_bf16 v[32:35], v[164:167], v[198:201], v[32:35]
	v_mfma_f32_16x16x32_bf16 v[20:23], v[156:159], v[206:209], v[20:23]
	v_mfma_f32_16x16x32_bf16 v[16:19], v[164:167], v[206:209], v[16:19]
	v_mfma_f32_16x16x32_bf16 v[8:11], v[156:159], v[214:217], v[8:11]
	v_mfma_f32_16x16x32_bf16 v[0:3], v[164:167], v[214:217], v[0:3]
	v_mfma_f32_16x16x32_bf16 v[52:55], v[160:163], v[194:197], v[52:55]
	v_mfma_f32_16x16x32_bf16 v[48:51], v[168:171], v[194:197], v[48:51]
	v_mfma_f32_16x16x32_bf16 v[36:39], v[160:163], v[202:205], v[36:39]
	v_mfma_f32_16x16x32_bf16 v[32:35], v[168:171], v[202:205], v[32:35]
	v_mfma_f32_16x16x32_bf16 v[20:23], v[160:163], v[210:213], v[20:23]
	v_mfma_f32_16x16x32_bf16 v[16:19], v[168:171], v[210:213], v[16:19]
	v_mfma_f32_16x16x32_bf16 v[8:11], v[160:163], v[218:221], v[8:11]
	v_mfma_f32_16x16x32_bf16 v[0:3], v[168:171], v[218:221], v[0:3]
	v_mfma_f32_16x16x32_bf16 v[60:63], v[172:175], v[190:193], v[60:63]
	v_mfma_f32_16x16x32_bf16 v[56:59], v[180:183], v[190:193], v[56:59]
	v_mfma_f32_16x16x32_bf16 v[44:47], v[172:175], v[198:201], v[44:47]
	v_mfma_f32_16x16x32_bf16 v[40:43], v[180:183], v[198:201], v[40:43]
	v_mfma_f32_16x16x32_bf16 v[28:31], v[172:175], v[206:209], v[28:31]
	v_mfma_f32_16x16x32_bf16 v[24:27], v[180:183], v[206:209], v[24:27]
	v_mfma_f32_16x16x32_bf16 v[12:15], v[172:175], v[214:217], v[12:15]
	v_mfma_f32_16x16x32_bf16 v[4:7], v[180:183], v[214:217], v[4:7]
	v_mfma_f32_16x16x32_bf16 v[60:63], v[176:179], v[194:197], v[60:63]
	v_mfma_f32_16x16x32_bf16 v[56:59], v[184:187], v[194:197], v[56:59]
	v_mfma_f32_16x16x32_bf16 v[44:47], v[176:179], v[202:205], v[44:47]
	v_mfma_f32_16x16x32_bf16 v[40:43], v[184:187], v[202:205], v[40:43]
	v_mfma_f32_16x16x32_bf16 v[28:31], v[176:179], v[210:213], v[28:31]
	v_mfma_f32_16x16x32_bf16 v[24:27], v[184:187], v[210:213], v[24:27]
	v_mfma_f32_16x16x32_bf16 v[12:15], v[176:179], v[218:221], v[12:15]
	v_mfma_f32_16x16x32_bf16 v[4:7], v[184:187], v[218:221], v[4:7]
	s_barrier
	s_add_i32 s48, s48, 2
	s_add_u32 s20, s20, 0x100
	s_addc_u32 s21, s21, 0
	s_add_u32 s46, s46, 0x100
	s_addc_u32 s47, s47, 0
	s_cmp_gt_u32 s48, 29
	s_cbranch_scc0 .LBB0_1539
	s_and_b64 vcc, exec, s[8:9]
	s_cbranch_vccz .LBB0_1542
	s_barrier

.LBB0_1624:
	s_setprio 2
	ds_read_b128 v[128:131], v177
	ds_read_b128 v[132:135], v177 offset:1024
	ds_read_b128 v[136:139], v177 offset:2048
	ds_read_b128 v[140:143], v177 offset:3072
	ds_read_b128 v[160:163], v178
	ds_read_b128 v[164:167], v178 offset:1024
	ds_read_b128 v[168:171], v178 offset:2048
	ds_read_b128 v[182:185], v178 offset:3072
	s_add_u32 s20, s18, 0xffea0080
	s_addc_u32 s21, s19, -1
	s_cmpk_eq_i32 s48, 0x54
	s_cselect_b32 s23, s1, s21
	s_cselect_b32 s22, s0, s20
	s_cselect_b32 s21, s17, s47
	s_cselect_b32 s20, s16, s46
	v_lshl_add_u64 v[172:173], s[18:19], 0, v[152:153]
	s_add_i32 m0, s27, 0xc000
	ds_read_b128 v[190:193], v179
	ds_read_b128 v[194:197], v179 offset:1024
	ds_read_b128 v[198:201], v179 offset:2048
	ds_read_b128 v[202:205], v179 offset:3072
	ds_read_b128 v[206:209], v179 offset:4096
	ds_read_b128 v[210:213], v179 offset:5120
	ds_read_b128 v[214:217], v179 offset:6144
	ds_read_b128 v[218:221], v179 offset:7168
	s_setprio 0
	global_load_lds_dwordx4 v[172:173], off
	v_lshl_add_u64 v[172:173], s[18:19], 0, v[154:155]
	s_add_i32 m0, s27, 0xe000
	s_nop 0
	global_load_lds_dwordx4 v[172:173], off
	s_waitcnt vmcnt(8)
	s_waitcnt lgkmcnt(0)
	s_barrier
	s_waitcnt lgkmcnt(0)
	v_mfma_f32_16x16x32_bf16 v[124:127], v[128:131], v[190:193], v[124:127]
	v_mfma_f32_16x16x32_bf16 v[120:123], v[136:139], v[190:193], v[120:123]
	v_mfma_f32_16x16x32_bf16 v[108:111], v[128:131], v[198:201], v[108:111]
	v_mfma_f32_16x16x32_bf16 v[104:107], v[136:139], v[198:201], v[104:107]
	v_mfma_f32_16x16x32_bf16 v[92:95], v[128:131], v[206:209], v[92:95]
	v_mfma_f32_16x16x32_bf16 v[88:91], v[136:139], v[206:209], v[88:91]
	v_mfma_f32_16x16x32_bf16 v[76:79], v[128:131], v[214:217], v[76:79]
	v_mfma_f32_16x16x32_bf16 v[72:75], v[136:139], v[214:217], v[72:75]
	v_mfma_f32_16x16x32_bf16 v[124:127], v[132:135], v[194:197], v[124:127]
	v_mfma_f32_16x16x32_bf16 v[120:123], v[140:143], v[194:197], v[120:123]
	v_mfma_f32_16x16x32_bf16 v[108:111], v[132:135], v[202:205], v[108:111]
	v_mfma_f32_16x16x32_bf16 v[104:107], v[140:143], v[202:205], v[104:107]
	v_mfma_f32_16x16x32_bf16 v[92:95], v[132:135], v[210:213], v[92:95]
	v_mfma_f32_16x16x32_bf16 v[88:91], v[140:143], v[210:213], v[88:91]
	v_mfma_f32_16x16x32_bf16 v[76:79], v[132:135], v[218:221], v[76:79]
	v_mfma_f32_16x16x32_bf16 v[72:75], v[140:143], v[218:221], v[72:75]
	v_mfma_f32_16x16x32_bf16 v[116:119], v[160:163], v[190:193], v[116:119]
	v_mfma_f32_16x16x32_bf16 v[112:115], v[168:171], v[190:193], v[112:115]
	v_mfma_f32_16x16x32_bf16 v[100:103], v[160:163], v[198:201], v[100:103]
	v_mfma_f32_16x16x32_bf16 v[96:99], v[168:171], v[198:201], v[96:99]
	v_mfma_f32_16x16x32_bf16 v[84:87], v[160:163], v[206:209], v[84:87]
	v_mfma_f32_16x16x32_bf16 v[80:83], v[168:171], v[206:209], v[80:83]
	v_mfma_f32_16x16x32_bf16 v[68:71], v[160:163], v[214:217], v[68:71]
	v_mfma_f32_16x16x32_bf16 v[64:67], v[168:171], v[214:217], v[64:67]
	v_mfma_f32_16x16x32_bf16 v[116:119], v[164:167], v[194:197], v[116:119]
	v_mfma_f32_16x16x32_bf16 v[112:115], v[182:185], v[194:197], v[112:115]
	v_mfma_f32_16x16x32_bf16 v[100:103], v[164:167], v[202:205], v[100:103]
	v_mfma_f32_16x16x32_bf16 v[96:99], v[182:185], v[202:205], v[96:99]
	v_mfma_f32_16x16x32_bf16 v[84:87], v[164:167], v[210:213], v[84:87]
	v_mfma_f32_16x16x32_bf16 v[80:83], v[182:185], v[210:213], v[80:83]
	v_mfma_f32_16x16x32_bf16 v[68:71], v[164:167], v[218:221], v[68:71]
	v_mfma_f32_16x16x32_bf16 v[64:67], v[182:185], v[218:221], v[64:67]
	s_barrier
	s_add_i32 s49, s39, s26
	v_lshl_add_u64 v[172:173], s[20:21], 0, v[146:147]
	s_mov_b32 m0, s49
	s_setprio 2
	ds_read_b128 v[190:193], v179 offset:16384
	ds_read_b128 v[194:197], v179 offset:17408
	ds_read_b128 v[198:201], v179 offset:18432
	ds_read_b128 v[202:205], v179 offset:19456
	ds_read_b128 v[206:209], v179 offset:20480
	ds_read_b128 v[210:213], v179 offset:21504
	ds_read_b128 v[214:217], v179 offset:22528
	ds_read_b128 v[218:221], v179 offset:23552
	s_setprio 0
	global_load_lds_dwordx4 v[172:173], off
	s_add_i32 m0, s49, 0x2000
	s_add_u32 s50, s20, 0x160000
	v_lshl_add_u64 v[186:187], s[20:21], 0, v[150:151]
	s_addc_u32 s51, s21, 0
	s_add_i32 s49, s40, s26
	global_load_lds_dwordx4 v[186:187], off
	v_lshl_add_u64 v[222:223], s[50:51], 0, v[146:147]
	s_mov_b32 m0, s49
	v_lshl_add_u64 v[224:225], s[22:23], 0, v[148:149]
	global_load_lds_dwordx4 v[222:223], off
	v_lshl_add_u64 v[222:223], s[50:51], 0, v[150:151]
	s_add_i32 m0, s49, 0x2000
	s_nop 0
	global_load_lds_dwordx4 v[222:223], off
	v_lshl_add_u64 v[222:223], s[22:23], 0, v[144:145]
	s_mov_b32 m0, s27
	s_nop 0
	global_load_lds_dwordx4 v[222:223], off
	s_mov_b32 m0, s28
	s_nop 0
	global_load_lds_dwordx4 v[224:225], off
	s_waitcnt vmcnt(8)
	s_waitcnt lgkmcnt(0)
	s_barrier
	s_waitcnt lgkmcnt(0)
	v_mfma_f32_16x16x32_bf16 v[60:63], v[128:131], v[190:193], v[60:63]
	v_mfma_f32_16x16x32_bf16 v[56:59], v[136:139], v[190:193], v[56:59]
	v_mfma_f32_16x16x32_bf16 v[44:47], v[128:131], v[198:201], v[44:47]
	v_mfma_f32_16x16x32_bf16 v[40:43], v[136:139], v[198:201], v[40:43]
	v_mfma_f32_16x16x32_bf16 v[28:31], v[128:131], v[206:209], v[28:31]
	v_mfma_f32_16x16x32_bf16 v[24:27], v[136:139], v[206:209], v[24:27]
	v_mfma_f32_16x16x32_bf16 v[12:15], v[128:131], v[214:217], v[12:15]
	v_mfma_f32_16x16x32_bf16 v[8:11], v[136:139], v[214:217], v[8:11]
	v_mfma_f32_16x16x32_bf16 v[60:63], v[132:135], v[194:197], v[60:63]
	v_mfma_f32_16x16x32_bf16 v[56:59], v[140:143], v[194:197], v[56:59]
	v_mfma_f32_16x16x32_bf16 v[44:47], v[132:135], v[202:205], v[44:47]
	v_mfma_f32_16x16x32_bf16 v[40:43], v[140:143], v[202:205], v[40:43]
	v_mfma_f32_16x16x32_bf16 v[28:31], v[132:135], v[210:213], v[28:31]
	v_mfma_f32_16x16x32_bf16 v[24:27], v[140:143], v[210:213], v[24:27]
	v_mfma_f32_16x16x32_bf16 v[12:15], v[132:135], v[218:221], v[12:15]
	v_mfma_f32_16x16x32_bf16 v[8:11], v[140:143], v[218:221], v[8:11]
	v_mfma_f32_16x16x32_bf16 v[52:55], v[160:163], v[190:193], v[52:55]
	v_mfma_f32_16x16x32_bf16 v[48:51], v[168:171], v[190:193], v[48:51]
	v_mfma_f32_16x16x32_bf16 v[36:39], v[160:163], v[198:201], v[36:39]
	v_mfma_f32_16x16x32_bf16 v[32:35], v[168:171], v[198:201], v[32:35]
	v_mfma_f32_16x16x32_bf16 v[20:23], v[160:163], v[206:209], v[20:23]
	v_mfma_f32_16x16x32_bf16 v[16:19], v[168:171], v[206:209], v[16:19]
	v_mfma_f32_16x16x32_bf16 v[4:7], v[160:163], v[214:217], v[4:7]
	v_mfma_f32_16x16x32_bf16 v[0:3], v[168:171], v[214:217], v[0:3]
	v_mfma_f32_16x16x32_bf16 v[52:55], v[164:167], v[194:197], v[52:55]
	v_mfma_f32_16x16x32_bf16 v[48:51], v[182:185], v[194:197], v[48:51]
	v_mfma_f32_16x16x32_bf16 v[36:39], v[164:167], v[202:205], v[36:39]
	v_mfma_f32_16x16x32_bf16 v[32:35], v[182:185], v[202:205], v[32:35]
	v_mfma_f32_16x16x32_bf16 v[20:23], v[164:167], v[210:213], v[20:23]
	v_mfma_f32_16x16x32_bf16 v[16:19], v[182:185], v[210:213], v[16:19]
	v_mfma_f32_16x16x32_bf16 v[4:7], v[164:167], v[218:221], v[4:7]
	v_mfma_f32_16x16x32_bf16 v[0:3], v[182:185], v[218:221], v[0:3]
	s_barrier
	s_add_i32 s49, 0, 0x18000
	s_add_i32 s50, 0, 0x1c000
	v_add_u32_e32 v140, s49, v175
	v_add_u32_e32 v181, s50, v175
	s_setprio 2
	ds_read_b128 v[128:131], v140
	ds_read_b128 v[132:135], v140 offset:1024
	ds_read_b128 v[136:139], v140 offset:2048
	ds_read_b128 v[140:143], v140 offset:3072
	ds_read_b128 v[160:163], v181
	ds_read_b128 v[164:167], v181 offset:1024
	ds_read_b128 v[168:171], v181 offset:2048
	ds_read_b128 v[182:185], v181 offset:3072
	s_add_u32 s22, s22, 0x160000
	s_addc_u32 s23, s23, 0
	s_mov_b32 m0, s29
	v_lshl_add_u64 v[226:227], s[22:23], 0, v[144:145]
	ds_read_b128 v[190:193], v179 offset:32768
	ds_read_b128 v[194:197], v179 offset:33792
	ds_read_b128 v[198:201], v179 offset:34816
	ds_read_b128 v[202:205], v179 offset:35840
	ds_read_b128 v[206:209], v179 offset:36864
	ds_read_b128 v[210:213], v179 offset:37888
	ds_read_b128 v[214:217], v179 offset:38912
	ds_read_b128 v[218:221], v179 offset:39936
	s_setprio 0
	global_load_lds_dwordx4 v[226:227], off
	v_lshl_add_u64 v[226:227], s[22:23], 0, v[148:149]
	s_mov_b32 m0, s30
	s_nop 0
	global_load_lds_dwordx4 v[226:227], off
	s_waitcnt vmcnt(8)
	s_waitcnt lgkmcnt(0)
	s_barrier
	s_waitcnt lgkmcnt(0)
	v_mfma_f32_16x16x32_bf16 v[124:127], v[128:131], v[190:193], v[124:127]
	v_mfma_f32_16x16x32_bf16 v[120:123], v[136:139], v[190:193], v[120:123]
	v_mfma_f32_16x16x32_bf16 v[108:111], v[128:131], v[198:201], v[108:111]
	v_mfma_f32_16x16x32_bf16 v[104:107], v[136:139], v[198:201], v[104:107]
	v_mfma_f32_16x16x32_bf16 v[92:95], v[128:131], v[206:209], v[92:95]
	v_mfma_f32_16x16x32_bf16 v[88:91], v[136:139], v[206:209], v[88:91]
	v_mfma_f32_16x16x32_bf16 v[76:79], v[128:131], v[214:217], v[76:79]
	v_mfma_f32_16x16x32_bf16 v[72:75], v[136:139], v[214:217], v[72:75]
	v_mfma_f32_16x16x32_bf16 v[124:127], v[132:135], v[194:197], v[124:127]
	v_mfma_f32_16x16x32_bf16 v[120:123], v[140:143], v[194:197], v[120:123]
	v_mfma_f32_16x16x32_bf16 v[108:111], v[132:135], v[202:205], v[108:111]
	v_mfma_f32_16x16x32_bf16 v[104:107], v[140:143], v[202:205], v[104:107]
	v_mfma_f32_16x16x32_bf16 v[92:95], v[132:135], v[210:213], v[92:95]
	v_mfma_f32_16x16x32_bf16 v[88:91], v[140:143], v[210:213], v[88:91]
	v_mfma_f32_16x16x32_bf16 v[76:79], v[132:135], v[218:221], v[76:79]
	v_mfma_f32_16x16x32_bf16 v[72:75], v[140:143], v[218:221], v[72:75]
	v_mfma_f32_16x16x32_bf16 v[116:119], v[160:163], v[190:193], v[116:119]
	v_mfma_f32_16x16x32_bf16 v[112:115], v[168:171], v[190:193], v[112:115]
	v_mfma_f32_16x16x32_bf16 v[100:103], v[160:163], v[198:201], v[100:103]
	v_mfma_f32_16x16x32_bf16 v[96:99], v[168:171], v[198:201], v[96:99]
	v_mfma_f32_16x16x32_bf16 v[84:87], v[160:163], v[206:209], v[84:87]
	v_mfma_f32_16x16x32_bf16 v[80:83], v[168:171], v[206:209], v[80:83]
	v_mfma_f32_16x16x32_bf16 v[68:71], v[160:163], v[214:217], v[68:71]
	v_mfma_f32_16x16x32_bf16 v[64:67], v[168:171], v[214:217], v[64:67]
	v_mfma_f32_16x16x32_bf16 v[116:119], v[164:167], v[194:197], v[116:119]
	v_mfma_f32_16x16x32_bf16 v[112:115], v[182:185], v[194:197], v[112:115]
	v_mfma_f32_16x16x32_bf16 v[100:103], v[164:167], v[202:205], v[100:103]
	v_mfma_f32_16x16x32_bf16 v[96:99], v[182:185], v[202:205], v[96:99]
	v_mfma_f32_16x16x32_bf16 v[84:87], v[164:167], v[210:213], v[84:87]
	v_mfma_f32_16x16x32_bf16 v[80:83], v[182:185], v[210:213], v[80:83]
	v_mfma_f32_16x16x32_bf16 v[68:71], v[164:167], v[218:221], v[68:71]
	v_mfma_f32_16x16x32_bf16 v[64:67], v[182:185], v[218:221], v[64:67]
	s_barrier
	s_add_i32 s22, s49, s26
	v_lshl_add_u64 v[172:173], v[172:173], 0, s[10:11]
	s_mov_b32 m0, s22
	s_setprio 2
	ds_read_b128 v[190:193], v179 offset:49152
	ds_read_b128 v[194:197], v179 offset:50176
	ds_read_b128 v[198:201], v179 offset:51200
	ds_read_b128 v[202:205], v179 offset:52224
	ds_read_b128 v[206:209], v179 offset:53248
	ds_read_b128 v[210:213], v179 offset:54272
	ds_read_b128 v[214:217], v179 offset:55296
	ds_read_b128 v[218:221], v179 offset:56320
	s_setprio 0
	global_load_lds_dwordx4 v[172:173], off
	s_add_i32 m0, s22, 0x2000
	s_add_u32 s20, s20, 0x160080
	v_lshl_add_u64 v[172:173], v[186:187], 0, s[10:11]
	s_addc_u32 s21, s21, 0
	s_add_i32 s22, s50, s26
	global_load_lds_dwordx4 v[172:173], off
	v_lshl_add_u64 v[172:173], s[20:21], 0, v[146:147]
	s_mov_b32 m0, s22
	s_nop 0
	global_load_lds_dwordx4 v[172:173], off
	v_lshl_add_u64 v[172:173], s[20:21], 0, v[150:151]
	s_add_i32 m0, s22, 0x2000
	s_nop 0
	global_load_lds_dwordx4 v[172:173], off
	v_lshl_add_u64 v[172:173], v[222:223], 0, s[10:11]
	s_mov_b32 m0, s35
	s_nop 0
	global_load_lds_dwordx4 v[172:173], off
	v_lshl_add_u64 v[172:173], v[224:225], 0, s[10:11]
	s_mov_b32 m0, s36
	s_nop 0
	global_load_lds_dwordx4 v[172:173], off
	s_waitcnt vmcnt(8)
	s_waitcnt lgkmcnt(0)
	s_barrier
	s_waitcnt lgkmcnt(0)
	v_mfma_f32_16x16x32_bf16 v[60:63], v[128:131], v[190:193], v[60:63]
	v_mfma_f32_16x16x32_bf16 v[56:59], v[136:139], v[190:193], v[56:59]
	v_mfma_f32_16x16x32_bf16 v[44:47], v[128:131], v[198:201], v[44:47]
	v_mfma_f32_16x16x32_bf16 v[40:43], v[136:139], v[198:201], v[40:43]
	v_mfma_f32_16x16x32_bf16 v[28:31], v[128:131], v[206:209], v[28:31]
	v_mfma_f32_16x16x32_bf16 v[24:27], v[136:139], v[206:209], v[24:27]
	v_mfma_f32_16x16x32_bf16 v[12:15], v[128:131], v[214:217], v[12:15]
	v_mfma_f32_16x16x32_bf16 v[8:11], v[136:139], v[214:217], v[8:11]
	v_mfma_f32_16x16x32_bf16 v[60:63], v[132:135], v[194:197], v[60:63]
	v_mfma_f32_16x16x32_bf16 v[56:59], v[140:143], v[194:197], v[56:59]
	v_mfma_f32_16x16x32_bf16 v[44:47], v[132:135], v[202:205], v[44:47]
	v_mfma_f32_16x16x32_bf16 v[40:43], v[140:143], v[202:205], v[40:43]
	v_mfma_f32_16x16x32_bf16 v[28:31], v[132:135], v[210:213], v[28:31]
	v_mfma_f32_16x16x32_bf16 v[24:27], v[140:143], v[210:213], v[24:27]
	v_mfma_f32_16x16x32_bf16 v[12:15], v[132:135], v[218:221], v[12:15]
	v_mfma_f32_16x16x32_bf16 v[8:11], v[140:143], v[218:221], v[8:11]
	v_mfma_f32_16x16x32_bf16 v[52:55], v[160:163], v[190:193], v[52:55]
	v_mfma_f32_16x16x32_bf16 v[48:51], v[168:171], v[190:193], v[48:51]
	v_mfma_f32_16x16x32_bf16 v[36:39], v[160:163], v[198:201], v[36:39]
	v_mfma_f32_16x16x32_bf16 v[32:35], v[168:171], v[198:201], v[32:35]
	v_mfma_f32_16x16x32_bf16 v[20:23], v[160:163], v[206:209], v[20:23]
	v_mfma_f32_16x16x32_bf16 v[16:19], v[168:171], v[206:209], v[16:19]
	v_mfma_f32_16x16x32_bf16 v[4:7], v[160:163], v[214:217], v[4:7]
	v_mfma_f32_16x16x32_bf16 v[0:3], v[168:171], v[214:217], v[0:3]
	v_mfma_f32_16x16x32_bf16 v[52:55], v[164:167], v[194:197], v[52:55]
	v_mfma_f32_16x16x32_bf16 v[48:51], v[182:185], v[194:197], v[48:51]
	v_mfma_f32_16x16x32_bf16 v[36:39], v[164:167], v[202:205], v[36:39]
	v_mfma_f32_16x16x32_bf16 v[32:35], v[182:185], v[202:205], v[32:35]
	v_mfma_f32_16x16x32_bf16 v[20:23], v[164:167], v[210:213], v[20:23]
	v_mfma_f32_16x16x32_bf16 v[16:19], v[182:185], v[210:213], v[16:19]
	v_mfma_f32_16x16x32_bf16 v[4:7], v[164:167], v[218:221], v[4:7]
	v_mfma_f32_16x16x32_bf16 v[0:3], v[182:185], v[218:221], v[0:3]
	s_barrier
	s_add_i32 s48, s48, 2
	s_add_u32 s18, s18, 0x100
	s_addc_u32 s19, s19, 0
	s_add_u32 s46, s46, 0x100
	s_addc_u32 s47, s47, 0
	s_cmpk_gt_u32 s48, 0x55
	s_cbranch_scc0 .LBB0_1624
	s_and_b64 vcc, exec, s[12:13]
	s_cbranch_vccz .LBB0_1627
	s_barrier
